# in-proj non-head epilogue rewritten: stage-wise sigmoid/silu over 8 elements, per-class code paths, no s_nop/cndmask
# baseline (speedup 1.0000x reference)
; DI u32x4 pack8(const float* x) { u32x4 v; v.x = cvt_pk(x[0], x[1]); v.y = cvt_pk(x[2], x[3]); v.z = cvt_pk(x[4], x[5]); v.w = cvt_pk(x[6], x[7]); return v; }
; DI float sigmoidf_(float v) { return __builtin_amdgcn_rcpf(1.0f + __expf(-v)); }
;     DI void operator()(const f32x4 (&acc)[2][2][4][2], const Unit& u, int wr, int wc, int fr, int fq) const {
;     ...
;         float rstd[2][4];
; #pragma unroll
;         for (int ai = 0; ai < 2; ++ai)
; #pragma unroll
;             for (int m = 0; m < 4; ++m) rstd[ai][m] = rsqrtf(ssq[row0 + ai * HALF + m * 16] * (1.0f / DM) + EPS);
;         if (u.pn < NHT) {
;     ...
; #pragma unroll
;         for (int bj = 0; bj < 2; ++bj) {
;             const int colw = u.pn * BM + bj * HALF + wc * 32;
;             const int act = colw < C_SILU ? 0 : (colw < C_GATE ? 1 : 2);
; #pragma unroll
;             for (int ai = 0; ai < 2; ++ai)
; #pragma unroll
;                 for (int m = 0; m < 4; ++m) {
;                     float v[8];
; #pragma unroll
;                     for (int j = 0; j < 4; ++j) { v[j] = acc[ai][bj][m][0][j] * rstd[ai][m]; v[4 + j] = acc[ai][bj][m][1][j] * rstd[ai][m]; }
;                     if (act) {
; #pragma unroll
;                         for (int j = 0; j < 8; ++j) { const float sg = sigmoidf_(v[j]); v[j] = act == 1 ? v[j] * sg : sg; }
;                     }
;                     *(u32x4*)(O + (size_t)(row0 + ai * HALF + m * 16) * LDP + col0 + bj * HALF) = pack8(v);
;                 }
;         }
.LBB0_133:
	s_lshl_b32 s4, s10, 8
	v_lshl_add_u32 v170, s2, 8, v147
	v_or_b32_e32 v130, s4, v197
	s_mov_b64 s[2:3], -1
	v_ashrrev_i32_e32 v171, 31, v170
	v_lshl_add_u64 v[132:133], v[170:171], 2, s[58:59]
	global_load_dword v172, v[132:133], off
	global_load_dword v168, v[132:133], off offset:64
	global_load_dword v166, v[132:133], off offset:128
	global_load_dword v164, v[132:133], off offset:192
	global_load_dword v162, v[132:133], off offset:512
	global_load_dword v160, v[132:133], off offset:576
	global_load_dword v158, v[132:133], off offset:640
	global_load_dword v128, v[132:133], off offset:704
	v_add_u32_e32 v222, 16, v170
	v_add_u32_e32 v211, 32, v170
	v_add_u32_e32 v209, 48, v170
	v_add_u32_e32 v207, 0x80, v170
	v_add_u32_e32 v205, 0x90, v170
	v_add_u32_e32 v203, 0xa0, v170
	v_add_u32_e32 v201, 0xb0, v170
	v_ashrrev_i32_e32 v223, 31, v222
	v_ashrrev_i32_e32 v221, 31, v211
	v_ashrrev_i32_e32 v210, 31, v209
	v_ashrrev_i32_e32 v208, 31, v207
	v_ashrrev_i32_e32 v206, 31, v205
	v_ashrrev_i32_e32 v204, 31, v203
	v_ashrrev_i32_e32 v202, 31, v201
	s_cmp_lt_i32 s10, 19
	s_waitcnt vmcnt(0)
	v_fmamk_f32 v172, v172, 0x3a000000, v218
	v_cmp_gt_f32_e32 vcc, s33, v172
	v_mul_f32_e32 v131, 0x4b800000, v172
	s_nop 0
	v_cndmask_b32_e32 v172, v172, v131, vcc
	v_rsq_f32_e32 v172, v172
	s_nop 0
	v_mul_f32_e32 v131, 0x45800000, v172
	v_cndmask_b32_e32 v172, v172, v131, vcc
	v_fmamk_f32 v168, v168, 0x3a000000, v218
	v_cmp_gt_f32_e32 vcc, s33, v168
	v_mul_f32_e32 v131, 0x4b800000, v168
	s_nop 0
	v_cndmask_b32_e32 v168, v168, v131, vcc
	v_rsq_f32_e32 v168, v168
	s_nop 0
	v_mul_f32_e32 v131, 0x45800000, v168
	v_cndmask_b32_e32 v168, v168, v131, vcc
	v_fmamk_f32 v166, v166, 0x3a000000, v218
	v_cmp_gt_f32_e32 vcc, s33, v166
	v_mul_f32_e32 v131, 0x4b800000, v166
	s_nop 0
	v_cndmask_b32_e32 v166, v166, v131, vcc
	v_rsq_f32_e32 v166, v166
	s_nop 0
	v_mul_f32_e32 v131, 0x45800000, v166
	v_cndmask_b32_e32 v166, v166, v131, vcc
	v_fmamk_f32 v164, v164, 0x3a000000, v218
	v_cmp_gt_f32_e32 vcc, s33, v164
	v_mul_f32_e32 v131, 0x4b800000, v164
	s_nop 0
	v_cndmask_b32_e32 v164, v164, v131, vcc
	v_rsq_f32_e32 v164, v164
	s_nop 0
	v_mul_f32_e32 v131, 0x45800000, v164
	v_cndmask_b32_e32 v164, v164, v131, vcc
	v_fmamk_f32 v162, v162, 0x3a000000, v218
	v_cmp_gt_f32_e32 vcc, s33, v162
	v_mul_f32_e32 v131, 0x4b800000, v162
	s_nop 0
	v_cndmask_b32_e32 v162, v162, v131, vcc
	v_rsq_f32_e32 v162, v162
	s_nop 0
	v_mul_f32_e32 v131, 0x45800000, v162
	v_cndmask_b32_e32 v162, v162, v131, vcc
	v_fmamk_f32 v160, v160, 0x3a000000, v218
	v_cmp_gt_f32_e32 vcc, s33, v160
	v_mul_f32_e32 v131, 0x4b800000, v160
	s_nop 0
	v_cndmask_b32_e32 v160, v160, v131, vcc
	v_rsq_f32_e32 v160, v160
	s_nop 0
	v_mul_f32_e32 v131, 0x45800000, v160
	v_cndmask_b32_e32 v160, v160, v131, vcc
	v_fmamk_f32 v158, v158, 0x3a000000, v218
	v_cmp_gt_f32_e32 vcc, s33, v158
	v_mul_f32_e32 v131, 0x4b800000, v158
	s_nop 0
	v_cndmask_b32_e32 v158, v158, v131, vcc
	v_rsq_f32_e32 v158, v158
	s_nop 0
	v_mul_f32_e32 v131, 0x45800000, v158
	v_cndmask_b32_e32 v158, v158, v131, vcc
	v_fmamk_f32 v128, v128, 0x3a000000, v218
	v_cmp_gt_f32_e32 vcc, s33, v128
	v_mul_f32_e32 v131, 0x4b800000, v128
	s_nop 0
	v_cndmask_b32_e32 v128, v128, v131, vcc
	v_rsq_f32_e32 v128, v128
	s_nop 0
	v_mul_f32_e32 v131, 0x45800000, v128
	v_cndmask_b32_e32 v156, v128, v131, vcc
	s_cbranch_scc1 .LBB0_199
	s_or_b32 s8, s4, s83
	s_mov_b32 s5, 0xbfb8aa3b
	s_mov_b32 s6, 0x8c000
	s_mov_b32 s7, 0
	s_mov_b32 s2, 0x2bc000
	s_mov_b32 s3, 0
	v_mov_b64_e32 v[132:133], s[56:57]
	v_mad_i64_i32 v[132:133], vcc, v170, s68, v[132:133]
	v_mov_b32_e32 v131, 0
	v_lshl_add_u64 v[132:133], v[130:131], 1, v[132:133]
	v_mov_b64_e32 v[134:135], v[132:133]
	s_cmpk_lt_i32 s8, 0x1da0
	s_cbranch_scc1 .Lp2e_b0_act0
	s_cmpk_lt_i32 s8, 0x25a0
	s_cbranch_scc1 .Lp2e_b0_act1
	v_mul_f32_e32 v176, v124, v172
	v_mul_f32_e32 v177, v125, v172
	v_mul_f32_e32 v178, v126, v172
	v_mul_f32_e32 v179, v127, v172
	v_mul_f32_e32 v180, v120, v172
	v_mul_f32_e32 v181, v121, v172
	v_mul_f32_e32 v182, v122, v172
	v_mul_f32_e32 v183, v123, v172
	v_mul_f32_e32 v176, s5, v176
	v_mul_f32_e32 v177, s5, v177
	v_mul_f32_e32 v178, s5, v178
	v_mul_f32_e32 v179, s5, v179
	v_mul_f32_e32 v180, s5, v180
	v_mul_f32_e32 v181, s5, v181
	v_mul_f32_e32 v182, s5, v182
	v_mul_f32_e32 v183, s5, v183
	v_exp_f32_e32 v176, v176
	v_exp_f32_e32 v177, v177
	v_exp_f32_e32 v178, v178
	v_exp_f32_e32 v179, v179
	v_exp_f32_e32 v180, v180
	v_exp_f32_e32 v181, v181
	v_exp_f32_e32 v182, v182
	v_exp_f32_e32 v183, v183
	v_add_f32_e32 v176, 1.0, v176
	v_add_f32_e32 v177, 1.0, v177
	v_add_f32_e32 v178, 1.0, v178
	v_add_f32_e32 v179, 1.0, v179
	v_add_f32_e32 v180, 1.0, v180
	v_add_f32_e32 v181, 1.0, v181
	v_add_f32_e32 v182, 1.0, v182
	v_add_f32_e32 v183, 1.0, v183
	v_rcp_f32_e32 v176, v176
	v_rcp_f32_e32 v177, v177
	v_rcp_f32_e32 v178, v178
	v_rcp_f32_e32 v179, v179
	v_rcp_f32_e32 v180, v180
	v_rcp_f32_e32 v181, v181
	v_rcp_f32_e32 v182, v182
	v_rcp_f32_e32 v183, v183
	v_cvt_pk_bf16_f32 v184, v176, v177
	v_cvt_pk_bf16_f32 v185, v178, v179
	v_cvt_pk_bf16_f32 v186, v180, v181
	v_cvt_pk_bf16_f32 v187, v182, v183
	global_store_dwordx4 v[134:135], v[184:187], off
	v_lshl_add_u64 v[134:135], v[134:135], 0, s[6:7]
	v_mul_f32_e32 v202, v108, v168
	v_mul_f32_e32 v203, v109, v168
	v_mul_f32_e32 v204, v110, v168
	v_mul_f32_e32 v205, v111, v168
	v_mul_f32_e32 v206, v104, v168
	v_mul_f32_e32 v207, v105, v168
	v_mul_f32_e32 v208, v106, v168
	v_mul_f32_e32 v209, v107, v168
	v_mul_f32_e32 v202, s5, v202
	v_mul_f32_e32 v203, s5, v203
	v_mul_f32_e32 v204, s5, v204
	v_mul_f32_e32 v205, s5, v205
	v_mul_f32_e32 v206, s5, v206
	v_mul_f32_e32 v207, s5, v207
; DI u32x4 pack8(const float* x) { u32x4 v; v.x = cvt_pk(x[0], x[1]); v.y = cvt_pk(x[2], x[3]); v.z = cvt_pk(x[4], x[5]); v.w = cvt_pk(x[6], x[7]); return v; }
; DI float sigmoidf_(float v) { return __builtin_amdgcn_rcpf(1.0f + __expf(-v)); }
;     DI void operator()(const f32x4 (&acc)[2][2][4][2], const Unit& u, int wr, int wc, int fr, int fq) const {
;     ...
;         for (int bj = 0; bj < 2; ++bj) {
;             const int colw = u.pn * BM + bj * HALF + wc * 32;
;             const int act = colw < C_SILU ? 0 : (colw < C_GATE ? 1 : 2);
; #pragma unroll
;             for (int ai = 0; ai < 2; ++ai)
; #pragma unroll
;                 for (int m = 0; m < 4; ++m) {
;                     float v[8];
; #pragma unroll
;                     for (int j = 0; j < 4; ++j) { v[j] = acc[ai][bj][m][0][j] * rstd[ai][m]; v[4 + j] = acc[ai][bj][m][1][j] * rstd[ai][m]; }
;                     if (act) {
; #pragma unroll
;                         for (int j = 0; j < 8; ++j) { const float sg = sigmoidf_(v[j]); v[j] = act == 1 ? v[j] * sg : sg; }
;                     }
;                     *(u32x4*)(O + (size_t)(row0 + ai * HALF + m * 16) * LDP + col0 + bj * HALF) = pack8(v);
;                 }
	v_mul_f32_e32 v208, s5, v208
	v_mul_f32_e32 v209, s5, v209
	v_exp_f32_e32 v202, v202
	v_exp_f32_e32 v203, v203
	v_exp_f32_e32 v204, v204
	v_exp_f32_e32 v205, v205
	v_exp_f32_e32 v206, v206
	v_exp_f32_e32 v207, v207
	v_exp_f32_e32 v208, v208
	v_exp_f32_e32 v209, v209
	v_add_f32_e32 v202, 1.0, v202
	v_add_f32_e32 v203, 1.0, v203
	v_add_f32_e32 v204, 1.0, v204
	v_add_f32_e32 v205, 1.0, v205
	v_add_f32_e32 v206, 1.0, v206
	v_add_f32_e32 v207, 1.0, v207
	v_add_f32_e32 v208, 1.0, v208
	v_add_f32_e32 v209, 1.0, v209
	v_rcp_f32_e32 v202, v202
	v_rcp_f32_e32 v203, v203
	v_rcp_f32_e32 v204, v204
	v_rcp_f32_e32 v205, v205
	v_rcp_f32_e32 v206, v206
	v_rcp_f32_e32 v207, v207
	v_rcp_f32_e32 v208, v208
	v_rcp_f32_e32 v209, v209
	v_cvt_pk_bf16_f32 v228, v202, v203
	v_cvt_pk_bf16_f32 v229, v204, v205
	v_cvt_pk_bf16_f32 v230, v206, v207
	v_cvt_pk_bf16_f32 v231, v208, v209
	global_store_dwordx4 v[134:135], v[228:231], off
	v_lshl_add_u64 v[134:135], v[134:135], 0, s[6:7]
	v_mul_f32_e32 v176, v92, v166
	v_mul_f32_e32 v177, v93, v166
	v_mul_f32_e32 v178, v94, v166
	v_mul_f32_e32 v179, v95, v166
	v_mul_f32_e32 v180, v88, v166
	v_mul_f32_e32 v181, v89, v166
	v_mul_f32_e32 v182, v90, v166
	v_mul_f32_e32 v183, v91, v166
	v_mul_f32_e32 v176, s5, v176
	v_mul_f32_e32 v177, s5, v177
	v_mul_f32_e32 v178, s5, v178
	v_mul_f32_e32 v179, s5, v179
	v_mul_f32_e32 v180, s5, v180
	v_mul_f32_e32 v181, s5, v181
	v_mul_f32_e32 v182, s5, v182
	v_mul_f32_e32 v183, s5, v183
	v_exp_f32_e32 v176, v176
	v_exp_f32_e32 v177, v177
	v_exp_f32_e32 v178, v178
	v_exp_f32_e32 v179, v179
	v_exp_f32_e32 v180, v180
	v_exp_f32_e32 v181, v181
	v_exp_f32_e32 v182, v182
	v_exp_f32_e32 v183, v183
	v_add_f32_e32 v176, 1.0, v176
	v_add_f32_e32 v177, 1.0, v177
	v_add_f32_e32 v178, 1.0, v178
	v_add_f32_e32 v179, 1.0, v179
	v_add_f32_e32 v180, 1.0, v180
	v_add_f32_e32 v181, 1.0, v181
	v_add_f32_e32 v182, 1.0, v182
	v_add_f32_e32 v183, 1.0, v183
	v_rcp_f32_e32 v176, v176
	v_rcp_f32_e32 v177, v177
	v_rcp_f32_e32 v178, v178
	v_rcp_f32_e32 v179, v179
	v_rcp_f32_e32 v180, v180
	v_rcp_f32_e32 v181, v181
	v_rcp_f32_e32 v182, v182
	v_rcp_f32_e32 v183, v183
	v_cvt_pk_bf16_f32 v184, v176, v177
	v_cvt_pk_bf16_f32 v185, v178, v179
	v_cvt_pk_bf16_f32 v186, v180, v181
	v_cvt_pk_bf16_f32 v187, v182, v183
	global_store_dwordx4 v[134:135], v[184:187], off
	v_lshl_add_u64 v[134:135], v[134:135], 0, s[6:7]
	v_mul_f32_e32 v202, v76, v164
	v_mul_f32_e32 v203, v77, v164
	v_mul_f32_e32 v204, v78, v164
	v_mul_f32_e32 v205, v79, v164
	v_mul_f32_e32 v206, v72, v164
	v_mul_f32_e32 v207, v73, v164
	v_mul_f32_e32 v208, v74, v164
	v_mul_f32_e32 v209, v75, v164
	v_mul_f32_e32 v202, s5, v202
	v_mul_f32_e32 v203, s5, v203
	v_mul_f32_e32 v204, s5, v204
	v_mul_f32_e32 v205, s5, v205
	v_mul_f32_e32 v206, s5, v206
	v_mul_f32_e32 v207, s5, v207
	v_mul_f32_e32 v208, s5, v208
	v_mul_f32_e32 v209, s5, v209
	v_exp_f32_e32 v202, v202
	v_exp_f32_e32 v203, v203
	v_exp_f32_e32 v204, v204
	v_exp_f32_e32 v205, v205
	v_exp_f32_e32 v206, v206
	v_exp_f32_e32 v207, v207
	v_exp_f32_e32 v208, v208
	v_exp_f32_e32 v209, v209
	v_add_f32_e32 v202, 1.0, v202
	v_add_f32_e32 v203, 1.0, v203
	v_add_f32_e32 v204, 1.0, v204
	v_add_f32_e32 v205, 1.0, v205
	v_add_f32_e32 v206, 1.0, v206
	v_add_f32_e32 v207, 1.0, v207
	v_add_f32_e32 v208, 1.0, v208
	v_add_f32_e32 v209, 1.0, v209
	v_rcp_f32_e32 v202, v202
	v_rcp_f32_e32 v203, v203
	v_rcp_f32_e32 v204, v204
	v_rcp_f32_e32 v205, v205
	v_rcp_f32_e32 v206, v206
	v_rcp_f32_e32 v207, v207
	v_rcp_f32_e32 v208, v208
	v_rcp_f32_e32 v209, v209
	v_cvt_pk_bf16_f32 v228, v202, v203
	v_cvt_pk_bf16_f32 v229, v204, v205
	v_cvt_pk_bf16_f32 v230, v206, v207
	v_cvt_pk_bf16_f32 v231, v208, v209
	global_store_dwordx4 v[134:135], v[228:231], off
	v_lshl_add_u64 v[134:135], v[134:135], 0, s[2:3]
	v_mul_f32_e32 v176, v60, v162
	v_mul_f32_e32 v177, v61, v162
	v_mul_f32_e32 v178, v62, v162
	v_mul_f32_e32 v179, v63, v162
	v_mul_f32_e32 v180, v56, v162
	v_mul_f32_e32 v181, v57, v162
	v_mul_f32_e32 v182, v58, v162
	v_mul_f32_e32 v183, v59, v162
	v_mul_f32_e32 v176, s5, v176
	v_mul_f32_e32 v177, s5, v177
	v_mul_f32_e32 v178, s5, v178
	v_mul_f32_e32 v179, s5, v179
	v_mul_f32_e32 v180, s5, v180
	v_mul_f32_e32 v181, s5, v181
	v_mul_f32_e32 v182, s5, v182
	v_mul_f32_e32 v183, s5, v183
	v_exp_f32_e32 v176, v176
	v_exp_f32_e32 v177, v177
	v_exp_f32_e32 v178, v178
	v_exp_f32_e32 v179, v179
	v_exp_f32_e32 v180, v180
	v_exp_f32_e32 v181, v181
	v_exp_f32_e32 v182, v182
	v_exp_f32_e32 v183, v183
	v_add_f32_e32 v176, 1.0, v176
	v_add_f32_e32 v177, 1.0, v177
	v_add_f32_e32 v178, 1.0, v178
	v_add_f32_e32 v179, 1.0, v179
	v_add_f32_e32 v180, 1.0, v180
	v_add_f32_e32 v181, 1.0, v181
	v_add_f32_e32 v182, 1.0, v182
	v_add_f32_e32 v183, 1.0, v183
	v_rcp_f32_e32 v176, v176
	v_rcp_f32_e32 v177, v177
	v_rcp_f32_e32 v178, v178
	v_rcp_f32_e32 v179, v179
	v_rcp_f32_e32 v180, v180
	v_rcp_f32_e32 v181, v181
	v_rcp_f32_e32 v182, v182
	v_rcp_f32_e32 v183, v183
	v_cvt_pk_bf16_f32 v184, v176, v177
	v_cvt_pk_bf16_f32 v185, v178, v179
	v_cvt_pk_bf16_f32 v186, v180, v181
	v_cvt_pk_bf16_f32 v187, v182, v183
	global_store_dwordx4 v[134:135], v[184:187], off
	v_lshl_add_u64 v[134:135], v[134:135], 0, s[6:7]
	v_mul_f32_e32 v202, v44, v160
	v_mul_f32_e32 v203, v45, v160
	v_mul_f32_e32 v204, v46, v160
	v_mul_f32_e32 v205, v47, v160
	v_mul_f32_e32 v206, v40, v160
	v_mul_f32_e32 v207, v41, v160
	v_mul_f32_e32 v208, v42, v160
	v_mul_f32_e32 v209, v43, v160
	v_mul_f32_e32 v202, s5, v202
	v_mul_f32_e32 v203, s5, v203
	v_mul_f32_e32 v204, s5, v204
	v_mul_f32_e32 v205, s5, v205
	v_mul_f32_e32 v206, s5, v206
	v_mul_f32_e32 v207, s5, v207
	v_mul_f32_e32 v208, s5, v208
	v_mul_f32_e32 v209, s5, v209
; DI u32x4 pack8(const float* x) { u32x4 v; v.x = cvt_pk(x[0], x[1]); v.y = cvt_pk(x[2], x[3]); v.z = cvt_pk(x[4], x[5]); v.w = cvt_pk(x[6], x[7]); return v; }
; DI float sigmoidf_(float v) { return __builtin_amdgcn_rcpf(1.0f + __expf(-v)); }
;     DI void operator()(const f32x4 (&acc)[2][2][4][2], const Unit& u, int wr, int wc, int fr, int fq) const {
;     ...
;         for (int bj = 0; bj < 2; ++bj) {
;             const int colw = u.pn * BM + bj * HALF + wc * 32;
;             const int act = colw < C_SILU ? 0 : (colw < C_GATE ? 1 : 2);
; #pragma unroll
;             for (int ai = 0; ai < 2; ++ai)
; #pragma unroll
;                 for (int m = 0; m < 4; ++m) {
;                     float v[8];
; #pragma unroll
;                     for (int j = 0; j < 4; ++j) { v[j] = acc[ai][bj][m][0][j] * rstd[ai][m]; v[4 + j] = acc[ai][bj][m][1][j] * rstd[ai][m]; }
;                     if (act) {
; #pragma unroll
;                         for (int j = 0; j < 8; ++j) { const float sg = sigmoidf_(v[j]); v[j] = act == 1 ? v[j] * sg : sg; }
;                     }
;                     *(u32x4*)(O + (size_t)(row0 + ai * HALF + m * 16) * LDP + col0 + bj * HALF) = pack8(v);
;                 }
	v_exp_f32_e32 v202, v202
	v_exp_f32_e32 v203, v203
	v_exp_f32_e32 v204, v204
	v_exp_f32_e32 v205, v205
	v_exp_f32_e32 v206, v206
	v_exp_f32_e32 v207, v207
	v_exp_f32_e32 v208, v208
	v_exp_f32_e32 v209, v209
	v_add_f32_e32 v202, 1.0, v202
	v_add_f32_e32 v203, 1.0, v203
	v_add_f32_e32 v204, 1.0, v204
	v_add_f32_e32 v205, 1.0, v205
	v_add_f32_e32 v206, 1.0, v206
	v_add_f32_e32 v207, 1.0, v207
	v_add_f32_e32 v208, 1.0, v208
	v_add_f32_e32 v209, 1.0, v209
	v_rcp_f32_e32 v202, v202
	v_rcp_f32_e32 v203, v203
	v_rcp_f32_e32 v204, v204
	v_rcp_f32_e32 v205, v205
	v_rcp_f32_e32 v206, v206
	v_rcp_f32_e32 v207, v207
	v_rcp_f32_e32 v208, v208
	v_rcp_f32_e32 v209, v209
	v_cvt_pk_bf16_f32 v228, v202, v203
	v_cvt_pk_bf16_f32 v229, v204, v205
	v_cvt_pk_bf16_f32 v230, v206, v207
	v_cvt_pk_bf16_f32 v231, v208, v209
	global_store_dwordx4 v[134:135], v[228:231], off
	v_lshl_add_u64 v[134:135], v[134:135], 0, s[6:7]
	v_mul_f32_e32 v176, v28, v158
	v_mul_f32_e32 v177, v29, v158
	v_mul_f32_e32 v178, v30, v158
	v_mul_f32_e32 v179, v31, v158
	v_mul_f32_e32 v180, v24, v158
	v_mul_f32_e32 v181, v25, v158
	v_mul_f32_e32 v182, v26, v158
	v_mul_f32_e32 v183, v27, v158
	v_mul_f32_e32 v176, s5, v176
	v_mul_f32_e32 v177, s5, v177
	v_mul_f32_e32 v178, s5, v178
	v_mul_f32_e32 v179, s5, v179
	v_mul_f32_e32 v180, s5, v180
	v_mul_f32_e32 v181, s5, v181
	v_mul_f32_e32 v182, s5, v182
	v_mul_f32_e32 v183, s5, v183
	v_exp_f32_e32 v176, v176
	v_exp_f32_e32 v177, v177
	v_exp_f32_e32 v178, v178
	v_exp_f32_e32 v179, v179
	v_exp_f32_e32 v180, v180
	v_exp_f32_e32 v181, v181
	v_exp_f32_e32 v182, v182
	v_exp_f32_e32 v183, v183
	v_add_f32_e32 v176, 1.0, v176
	v_add_f32_e32 v177, 1.0, v177
	v_add_f32_e32 v178, 1.0, v178
	v_add_f32_e32 v179, 1.0, v179
	v_add_f32_e32 v180, 1.0, v180
	v_add_f32_e32 v181, 1.0, v181
	v_add_f32_e32 v182, 1.0, v182
	v_add_f32_e32 v183, 1.0, v183
	v_rcp_f32_e32 v176, v176
	v_rcp_f32_e32 v177, v177
	v_rcp_f32_e32 v178, v178
	v_rcp_f32_e32 v179, v179
	v_rcp_f32_e32 v180, v180
	v_rcp_f32_e32 v181, v181
	v_rcp_f32_e32 v182, v182
	v_rcp_f32_e32 v183, v183
	v_cvt_pk_bf16_f32 v184, v176, v177
	v_cvt_pk_bf16_f32 v185, v178, v179
	v_cvt_pk_bf16_f32 v186, v180, v181
	v_cvt_pk_bf16_f32 v187, v182, v183
	global_store_dwordx4 v[134:135], v[184:187], off
	v_lshl_add_u64 v[134:135], v[134:135], 0, s[6:7]
	v_mul_f32_e32 v202, v12, v156
	v_mul_f32_e32 v203, v13, v156
	v_mul_f32_e32 v204, v14, v156
	v_mul_f32_e32 v205, v15, v156
	v_mul_f32_e32 v206, v8, v156
	v_mul_f32_e32 v207, v9, v156
	v_mul_f32_e32 v208, v10, v156
	v_mul_f32_e32 v209, v11, v156
	v_mul_f32_e32 v202, s5, v202
	v_mul_f32_e32 v203, s5, v203
	v_mul_f32_e32 v204, s5, v204
	v_mul_f32_e32 v205, s5, v205
	v_mul_f32_e32 v206, s5, v206
	v_mul_f32_e32 v207, s5, v207
	v_mul_f32_e32 v208, s5, v208
	v_mul_f32_e32 v209, s5, v209
	v_exp_f32_e32 v202, v202
	v_exp_f32_e32 v203, v203
	v_exp_f32_e32 v204, v204
	v_exp_f32_e32 v205, v205
	v_exp_f32_e32 v206, v206
	v_exp_f32_e32 v207, v207
	v_exp_f32_e32 v208, v208
	v_exp_f32_e32 v209, v209
	v_add_f32_e32 v202, 1.0, v202
	v_add_f32_e32 v203, 1.0, v203
	v_add_f32_e32 v204, 1.0, v204
	v_add_f32_e32 v205, 1.0, v205
	v_add_f32_e32 v206, 1.0, v206
	v_add_f32_e32 v207, 1.0, v207
	v_add_f32_e32 v208, 1.0, v208
	v_add_f32_e32 v209, 1.0, v209
	v_rcp_f32_e32 v202, v202
	v_rcp_f32_e32 v203, v203
	v_rcp_f32_e32 v204, v204
	v_rcp_f32_e32 v205, v205
	v_rcp_f32_e32 v206, v206
	v_rcp_f32_e32 v207, v207
	v_rcp_f32_e32 v208, v208
	v_rcp_f32_e32 v209, v209
	v_cvt_pk_bf16_f32 v228, v202, v203
	v_cvt_pk_bf16_f32 v229, v204, v205
	v_cvt_pk_bf16_f32 v230, v206, v207
	v_cvt_pk_bf16_f32 v231, v208, v209
	global_store_dwordx4 v[134:135], v[228:231], off
	s_branch .Lp2e_b0_done
.Lp2e_b0_act1:
	v_mul_f32_e32 v188, v124, v172
	v_mul_f32_e32 v189, v125, v172
	v_mul_f32_e32 v190, v126, v172
	v_mul_f32_e32 v191, v127, v172
	v_mul_f32_e32 v192, v120, v172
	v_mul_f32_e32 v193, v121, v172
	v_mul_f32_e32 v194, v122, v172
	v_mul_f32_e32 v195, v123, v172
	v_mul_f32_e32 v176, s5, v188
	v_mul_f32_e32 v177, s5, v189
	v_mul_f32_e32 v178, s5, v190
	v_mul_f32_e32 v179, s5, v191
	v_mul_f32_e32 v180, s5, v192
	v_mul_f32_e32 v181, s5, v193
	v_mul_f32_e32 v182, s5, v194
	v_mul_f32_e32 v183, s5, v195
	v_exp_f32_e32 v176, v176
	v_exp_f32_e32 v177, v177
	v_exp_f32_e32 v178, v178
	v_exp_f32_e32 v179, v179
	v_exp_f32_e32 v180, v180
	v_exp_f32_e32 v181, v181
	v_exp_f32_e32 v182, v182
	v_exp_f32_e32 v183, v183
	v_add_f32_e32 v176, 1.0, v176
	v_add_f32_e32 v177, 1.0, v177
	v_add_f32_e32 v178, 1.0, v178
	v_add_f32_e32 v179, 1.0, v179
	v_add_f32_e32 v180, 1.0, v180
	v_add_f32_e32 v181, 1.0, v181
	v_add_f32_e32 v182, 1.0, v182
	v_add_f32_e32 v183, 1.0, v183
	v_rcp_f32_e32 v176, v176
	v_rcp_f32_e32 v177, v177
	v_rcp_f32_e32 v178, v178
	v_rcp_f32_e32 v179, v179
	v_rcp_f32_e32 v180, v180
	v_rcp_f32_e32 v181, v181
	v_rcp_f32_e32 v182, v182
	v_rcp_f32_e32 v183, v183
	v_mul_f32_e32 v176, v188, v176
	v_mul_f32_e32 v177, v189, v177
	v_mul_f32_e32 v178, v190, v178
	v_mul_f32_e32 v179, v191, v179
	v_mul_f32_e32 v180, v192, v180
	v_mul_f32_e32 v181, v193, v181
	v_mul_f32_e32 v182, v194, v182
	v_mul_f32_e32 v183, v195, v183
	v_cvt_pk_bf16_f32 v184, v176, v177
	v_cvt_pk_bf16_f32 v185, v178, v179
	v_cvt_pk_bf16_f32 v186, v180, v181
	v_cvt_pk_bf16_f32 v187, v182, v183
	global_store_dwordx4 v[134:135], v[184:187], off
	v_lshl_add_u64 v[134:135], v[134:135], 0, s[6:7]
	v_mul_f32_e32 v222, v108, v168
	v_mul_f32_e32 v223, v109, v168
	v_mul_f32_e32 v224, v110, v168
	v_mul_f32_e32 v225, v111, v168
	v_mul_f32_e32 v226, v104, v168
	v_mul_f32_e32 v227, v105, v168
	v_mul_f32_e32 v232, v106, v168
	v_mul_f32_e32 v233, v107, v168
	v_mul_f32_e32 v202, s5, v222
; DI u32x4 pack8(const float* x) { u32x4 v; v.x = cvt_pk(x[0], x[1]); v.y = cvt_pk(x[2], x[3]); v.z = cvt_pk(x[4], x[5]); v.w = cvt_pk(x[6], x[7]); return v; }
; DI float sigmoidf_(float v) { return __builtin_amdgcn_rcpf(1.0f + __expf(-v)); }
;     DI void operator()(const f32x4 (&acc)[2][2][4][2], const Unit& u, int wr, int wc, int fr, int fq) const {
;     ...
;         for (int bj = 0; bj < 2; ++bj) {
;             const int colw = u.pn * BM + bj * HALF + wc * 32;
;             const int act = colw < C_SILU ? 0 : (colw < C_GATE ? 1 : 2);
; #pragma unroll
;             for (int ai = 0; ai < 2; ++ai)
; #pragma unroll
;                 for (int m = 0; m < 4; ++m) {
;                     float v[8];
; #pragma unroll
;                     for (int j = 0; j < 4; ++j) { v[j] = acc[ai][bj][m][0][j] * rstd[ai][m]; v[4 + j] = acc[ai][bj][m][1][j] * rstd[ai][m]; }
;                     if (act) {
; #pragma unroll
;                         for (int j = 0; j < 8; ++j) { const float sg = sigmoidf_(v[j]); v[j] = act == 1 ? v[j] * sg : sg; }
;                     }
;                     *(u32x4*)(O + (size_t)(row0 + ai * HALF + m * 16) * LDP + col0 + bj * HALF) = pack8(v);
;                 }
	v_mul_f32_e32 v203, s5, v223
	v_mul_f32_e32 v204, s5, v224
	v_mul_f32_e32 v205, s5, v225
	v_mul_f32_e32 v206, s5, v226
	v_mul_f32_e32 v207, s5, v227
	v_mul_f32_e32 v208, s5, v232
	v_mul_f32_e32 v209, s5, v233
	v_exp_f32_e32 v202, v202
	v_exp_f32_e32 v203, v203
	v_exp_f32_e32 v204, v204
	v_exp_f32_e32 v205, v205
	v_exp_f32_e32 v206, v206
	v_exp_f32_e32 v207, v207
	v_exp_f32_e32 v208, v208
	v_exp_f32_e32 v209, v209
	v_add_f32_e32 v202, 1.0, v202
	v_add_f32_e32 v203, 1.0, v203
	v_add_f32_e32 v204, 1.0, v204
	v_add_f32_e32 v205, 1.0, v205
	v_add_f32_e32 v206, 1.0, v206
	v_add_f32_e32 v207, 1.0, v207
	v_add_f32_e32 v208, 1.0, v208
	v_add_f32_e32 v209, 1.0, v209
	v_rcp_f32_e32 v202, v202
	v_rcp_f32_e32 v203, v203
	v_rcp_f32_e32 v204, v204
	v_rcp_f32_e32 v205, v205
	v_rcp_f32_e32 v206, v206
	v_rcp_f32_e32 v207, v207
	v_rcp_f32_e32 v208, v208
	v_rcp_f32_e32 v209, v209
	v_mul_f32_e32 v202, v222, v202
	v_mul_f32_e32 v203, v223, v203
	v_mul_f32_e32 v204, v224, v204
	v_mul_f32_e32 v205, v225, v205
	v_mul_f32_e32 v206, v226, v206
	v_mul_f32_e32 v207, v227, v207
	v_mul_f32_e32 v208, v232, v208
	v_mul_f32_e32 v209, v233, v209
	v_cvt_pk_bf16_f32 v228, v202, v203
	v_cvt_pk_bf16_f32 v229, v204, v205
	v_cvt_pk_bf16_f32 v230, v206, v207
	v_cvt_pk_bf16_f32 v231, v208, v209
	global_store_dwordx4 v[134:135], v[228:231], off
	v_lshl_add_u64 v[134:135], v[134:135], 0, s[6:7]
	v_mul_f32_e32 v188, v92, v166
	v_mul_f32_e32 v189, v93, v166
	v_mul_f32_e32 v190, v94, v166
	v_mul_f32_e32 v191, v95, v166
	v_mul_f32_e32 v192, v88, v166
	v_mul_f32_e32 v193, v89, v166
	v_mul_f32_e32 v194, v90, v166
	v_mul_f32_e32 v195, v91, v166
	v_mul_f32_e32 v176, s5, v188
	v_mul_f32_e32 v177, s5, v189
	v_mul_f32_e32 v178, s5, v190
	v_mul_f32_e32 v179, s5, v191
	v_mul_f32_e32 v180, s5, v192
	v_mul_f32_e32 v181, s5, v193
	v_mul_f32_e32 v182, s5, v194
	v_mul_f32_e32 v183, s5, v195
	v_exp_f32_e32 v176, v176
	v_exp_f32_e32 v177, v177
	v_exp_f32_e32 v178, v178
	v_exp_f32_e32 v179, v179
	v_exp_f32_e32 v180, v180
	v_exp_f32_e32 v181, v181
	v_exp_f32_e32 v182, v182
	v_exp_f32_e32 v183, v183
	v_add_f32_e32 v176, 1.0, v176
	v_add_f32_e32 v177, 1.0, v177
	v_add_f32_e32 v178, 1.0, v178
	v_add_f32_e32 v179, 1.0, v179
	v_add_f32_e32 v180, 1.0, v180
	v_add_f32_e32 v181, 1.0, v181
	v_add_f32_e32 v182, 1.0, v182
	v_add_f32_e32 v183, 1.0, v183
	v_rcp_f32_e32 v176, v176
	v_rcp_f32_e32 v177, v177
	v_rcp_f32_e32 v178, v178
	v_rcp_f32_e32 v179, v179
	v_rcp_f32_e32 v180, v180
	v_rcp_f32_e32 v181, v181
	v_rcp_f32_e32 v182, v182
	v_rcp_f32_e32 v183, v183
	v_mul_f32_e32 v176, v188, v176
	v_mul_f32_e32 v177, v189, v177
	v_mul_f32_e32 v178, v190, v178
	v_mul_f32_e32 v179, v191, v179
	v_mul_f32_e32 v180, v192, v180
	v_mul_f32_e32 v181, v193, v181
	v_mul_f32_e32 v182, v194, v182
	v_mul_f32_e32 v183, v195, v183
	v_cvt_pk_bf16_f32 v184, v176, v177
	v_cvt_pk_bf16_f32 v185, v178, v179
	v_cvt_pk_bf16_f32 v186, v180, v181
	v_cvt_pk_bf16_f32 v187, v182, v183
	global_store_dwordx4 v[134:135], v[184:187], off
	v_lshl_add_u64 v[134:135], v[134:135], 0, s[6:7]
	v_mul_f32_e32 v222, v76, v164
	v_mul_f32_e32 v223, v77, v164
	v_mul_f32_e32 v224, v78, v164
	v_mul_f32_e32 v225, v79, v164
	v_mul_f32_e32 v226, v72, v164
	v_mul_f32_e32 v227, v73, v164
	v_mul_f32_e32 v232, v74, v164
	v_mul_f32_e32 v233, v75, v164
	v_mul_f32_e32 v202, s5, v222
	v_mul_f32_e32 v203, s5, v223
	v_mul_f32_e32 v204, s5, v224
	v_mul_f32_e32 v205, s5, v225
	v_mul_f32_e32 v206, s5, v226
	v_mul_f32_e32 v207, s5, v227
	v_mul_f32_e32 v208, s5, v232
	v_mul_f32_e32 v209, s5, v233
	v_exp_f32_e32 v202, v202
	v_exp_f32_e32 v203, v203
	v_exp_f32_e32 v204, v204
	v_exp_f32_e32 v205, v205
	v_exp_f32_e32 v206, v206
	v_exp_f32_e32 v207, v207
	v_exp_f32_e32 v208, v208
	v_exp_f32_e32 v209, v209
	v_add_f32_e32 v202, 1.0, v202
	v_add_f32_e32 v203, 1.0, v203
	v_add_f32_e32 v204, 1.0, v204
	v_add_f32_e32 v205, 1.0, v205
	v_add_f32_e32 v206, 1.0, v206
	v_add_f32_e32 v207, 1.0, v207
	v_add_f32_e32 v208, 1.0, v208
	v_add_f32_e32 v209, 1.0, v209
	v_rcp_f32_e32 v202, v202
	v_rcp_f32_e32 v203, v203
	v_rcp_f32_e32 v204, v204
	v_rcp_f32_e32 v205, v205
	v_rcp_f32_e32 v206, v206
	v_rcp_f32_e32 v207, v207
	v_rcp_f32_e32 v208, v208
	v_rcp_f32_e32 v209, v209
	v_mul_f32_e32 v202, v222, v202
	v_mul_f32_e32 v203, v223, v203
	v_mul_f32_e32 v204, v224, v204
	v_mul_f32_e32 v205, v225, v205
	v_mul_f32_e32 v206, v226, v206
	v_mul_f32_e32 v207, v227, v207
	v_mul_f32_e32 v208, v232, v208
	v_mul_f32_e32 v209, v233, v209
	v_cvt_pk_bf16_f32 v228, v202, v203
	v_cvt_pk_bf16_f32 v229, v204, v205
	v_cvt_pk_bf16_f32 v230, v206, v207
	v_cvt_pk_bf16_f32 v231, v208, v209
	global_store_dwordx4 v[134:135], v[228:231], off
	v_lshl_add_u64 v[134:135], v[134:135], 0, s[2:3]
	v_mul_f32_e32 v188, v60, v162
	v_mul_f32_e32 v189, v61, v162
	v_mul_f32_e32 v190, v62, v162
	v_mul_f32_e32 v191, v63, v162
	v_mul_f32_e32 v192, v56, v162
	v_mul_f32_e32 v193, v57, v162
	v_mul_f32_e32 v194, v58, v162
	v_mul_f32_e32 v195, v59, v162
	v_mul_f32_e32 v176, s5, v188
	v_mul_f32_e32 v177, s5, v189
	v_mul_f32_e32 v178, s5, v190
	v_mul_f32_e32 v179, s5, v191
	v_mul_f32_e32 v180, s5, v192
	v_mul_f32_e32 v181, s5, v193
	v_mul_f32_e32 v182, s5, v194
	v_mul_f32_e32 v183, s5, v195
	v_exp_f32_e32 v176, v176
	v_exp_f32_e32 v177, v177
	v_exp_f32_e32 v178, v178
	v_exp_f32_e32 v179, v179
	v_exp_f32_e32 v180, v180
	v_exp_f32_e32 v181, v181
	v_exp_f32_e32 v182, v182
	v_exp_f32_e32 v183, v183
	v_add_f32_e32 v176, 1.0, v176
	v_add_f32_e32 v177, 1.0, v177
	v_add_f32_e32 v178, 1.0, v178
	v_add_f32_e32 v179, 1.0, v179
	v_add_f32_e32 v180, 1.0, v180
	v_add_f32_e32 v181, 1.0, v181
	v_add_f32_e32 v182, 1.0, v182
	v_add_f32_e32 v183, 1.0, v183
	v_rcp_f32_e32 v176, v176
; DI u32x4 pack8(const float* x) { u32x4 v; v.x = cvt_pk(x[0], x[1]); v.y = cvt_pk(x[2], x[3]); v.z = cvt_pk(x[4], x[5]); v.w = cvt_pk(x[6], x[7]); return v; }
; DI float sigmoidf_(float v) { return __builtin_amdgcn_rcpf(1.0f + __expf(-v)); }
;     DI void operator()(const f32x4 (&acc)[2][2][4][2], const Unit& u, int wr, int wc, int fr, int fq) const {
;     ...
;         for (int bj = 0; bj < 2; ++bj) {
;             const int colw = u.pn * BM + bj * HALF + wc * 32;
;             const int act = colw < C_SILU ? 0 : (colw < C_GATE ? 1 : 2);
; #pragma unroll
;             for (int ai = 0; ai < 2; ++ai)
; #pragma unroll
;                 for (int m = 0; m < 4; ++m) {
;                     float v[8];
; #pragma unroll
;                     for (int j = 0; j < 4; ++j) { v[j] = acc[ai][bj][m][0][j] * rstd[ai][m]; v[4 + j] = acc[ai][bj][m][1][j] * rstd[ai][m]; }
;                     if (act) {
; #pragma unroll
;                         for (int j = 0; j < 8; ++j) { const float sg = sigmoidf_(v[j]); v[j] = act == 1 ? v[j] * sg : sg; }
;                     }
;                     *(u32x4*)(O + (size_t)(row0 + ai * HALF + m * 16) * LDP + col0 + bj * HALF) = pack8(v);
;                 }
	v_rcp_f32_e32 v177, v177
	v_rcp_f32_e32 v178, v178
	v_rcp_f32_e32 v179, v179
	v_rcp_f32_e32 v180, v180
	v_rcp_f32_e32 v181, v181
	v_rcp_f32_e32 v182, v182
	v_rcp_f32_e32 v183, v183
	v_mul_f32_e32 v176, v188, v176
	v_mul_f32_e32 v177, v189, v177
	v_mul_f32_e32 v178, v190, v178
	v_mul_f32_e32 v179, v191, v179
	v_mul_f32_e32 v180, v192, v180
	v_mul_f32_e32 v181, v193, v181
	v_mul_f32_e32 v182, v194, v182
	v_mul_f32_e32 v183, v195, v183
	v_cvt_pk_bf16_f32 v184, v176, v177
	v_cvt_pk_bf16_f32 v185, v178, v179
	v_cvt_pk_bf16_f32 v186, v180, v181
	v_cvt_pk_bf16_f32 v187, v182, v183
	global_store_dwordx4 v[134:135], v[184:187], off
	v_lshl_add_u64 v[134:135], v[134:135], 0, s[6:7]
	v_mul_f32_e32 v222, v44, v160
	v_mul_f32_e32 v223, v45, v160
	v_mul_f32_e32 v224, v46, v160
	v_mul_f32_e32 v225, v47, v160
	v_mul_f32_e32 v226, v40, v160
	v_mul_f32_e32 v227, v41, v160
	v_mul_f32_e32 v232, v42, v160
	v_mul_f32_e32 v233, v43, v160
	v_mul_f32_e32 v202, s5, v222
	v_mul_f32_e32 v203, s5, v223
	v_mul_f32_e32 v204, s5, v224
	v_mul_f32_e32 v205, s5, v225
	v_mul_f32_e32 v206, s5, v226
	v_mul_f32_e32 v207, s5, v227
	v_mul_f32_e32 v208, s5, v232
	v_mul_f32_e32 v209, s5, v233
	v_exp_f32_e32 v202, v202
	v_exp_f32_e32 v203, v203
	v_exp_f32_e32 v204, v204
	v_exp_f32_e32 v205, v205
	v_exp_f32_e32 v206, v206
	v_exp_f32_e32 v207, v207
	v_exp_f32_e32 v208, v208
	v_exp_f32_e32 v209, v209
	v_add_f32_e32 v202, 1.0, v202
	v_add_f32_e32 v203, 1.0, v203
	v_add_f32_e32 v204, 1.0, v204
	v_add_f32_e32 v205, 1.0, v205
	v_add_f32_e32 v206, 1.0, v206
	v_add_f32_e32 v207, 1.0, v207
	v_add_f32_e32 v208, 1.0, v208
	v_add_f32_e32 v209, 1.0, v209
	v_rcp_f32_e32 v202, v202
	v_rcp_f32_e32 v203, v203
	v_rcp_f32_e32 v204, v204
	v_rcp_f32_e32 v205, v205
	v_rcp_f32_e32 v206, v206
	v_rcp_f32_e32 v207, v207
	v_rcp_f32_e32 v208, v208
	v_rcp_f32_e32 v209, v209
	v_mul_f32_e32 v202, v222, v202
	v_mul_f32_e32 v203, v223, v203
	v_mul_f32_e32 v204, v224, v204
	v_mul_f32_e32 v205, v225, v205
	v_mul_f32_e32 v206, v226, v206
	v_mul_f32_e32 v207, v227, v207
	v_mul_f32_e32 v208, v232, v208
	v_mul_f32_e32 v209, v233, v209
	v_cvt_pk_bf16_f32 v228, v202, v203
	v_cvt_pk_bf16_f32 v229, v204, v205
	v_cvt_pk_bf16_f32 v230, v206, v207
	v_cvt_pk_bf16_f32 v231, v208, v209
	global_store_dwordx4 v[134:135], v[228:231], off
	v_lshl_add_u64 v[134:135], v[134:135], 0, s[6:7]
	v_mul_f32_e32 v188, v28, v158
	v_mul_f32_e32 v189, v29, v158
	v_mul_f32_e32 v190, v30, v158
	v_mul_f32_e32 v191, v31, v158
	v_mul_f32_e32 v192, v24, v158
	v_mul_f32_e32 v193, v25, v158
	v_mul_f32_e32 v194, v26, v158
	v_mul_f32_e32 v195, v27, v158
	v_mul_f32_e32 v176, s5, v188
	v_mul_f32_e32 v177, s5, v189
	v_mul_f32_e32 v178, s5, v190
	v_mul_f32_e32 v179, s5, v191
	v_mul_f32_e32 v180, s5, v192
	v_mul_f32_e32 v181, s5, v193
	v_mul_f32_e32 v182, s5, v194
	v_mul_f32_e32 v183, s5, v195
	v_exp_f32_e32 v176, v176
	v_exp_f32_e32 v177, v177
	v_exp_f32_e32 v178, v178
	v_exp_f32_e32 v179, v179
	v_exp_f32_e32 v180, v180
	v_exp_f32_e32 v181, v181
	v_exp_f32_e32 v182, v182
	v_exp_f32_e32 v183, v183
	v_add_f32_e32 v176, 1.0, v176
	v_add_f32_e32 v177, 1.0, v177
	v_add_f32_e32 v178, 1.0, v178
	v_add_f32_e32 v179, 1.0, v179
	v_add_f32_e32 v180, 1.0, v180
	v_add_f32_e32 v181, 1.0, v181
	v_add_f32_e32 v182, 1.0, v182
	v_add_f32_e32 v183, 1.0, v183
	v_rcp_f32_e32 v176, v176
	v_rcp_f32_e32 v177, v177
	v_rcp_f32_e32 v178, v178
	v_rcp_f32_e32 v179, v179
	v_rcp_f32_e32 v180, v180
	v_rcp_f32_e32 v181, v181
	v_rcp_f32_e32 v182, v182
	v_rcp_f32_e32 v183, v183
	v_mul_f32_e32 v176, v188, v176
	v_mul_f32_e32 v177, v189, v177
	v_mul_f32_e32 v178, v190, v178
	v_mul_f32_e32 v179, v191, v179
	v_mul_f32_e32 v180, v192, v180
	v_mul_f32_e32 v181, v193, v181
	v_mul_f32_e32 v182, v194, v182
	v_mul_f32_e32 v183, v195, v183
	v_cvt_pk_bf16_f32 v184, v176, v177
	v_cvt_pk_bf16_f32 v185, v178, v179
	v_cvt_pk_bf16_f32 v186, v180, v181
	v_cvt_pk_bf16_f32 v187, v182, v183
	global_store_dwordx4 v[134:135], v[184:187], off
	v_lshl_add_u64 v[134:135], v[134:135], 0, s[6:7]
	v_mul_f32_e32 v222, v12, v156
	v_mul_f32_e32 v223, v13, v156
	v_mul_f32_e32 v224, v14, v156
	v_mul_f32_e32 v225, v15, v156
	v_mul_f32_e32 v226, v8, v156
	v_mul_f32_e32 v227, v9, v156
	v_mul_f32_e32 v232, v10, v156
	v_mul_f32_e32 v233, v11, v156
	v_mul_f32_e32 v202, s5, v222
	v_mul_f32_e32 v203, s5, v223
	v_mul_f32_e32 v204, s5, v224
	v_mul_f32_e32 v205, s5, v225
	v_mul_f32_e32 v206, s5, v226
	v_mul_f32_e32 v207, s5, v227
	v_mul_f32_e32 v208, s5, v232
	v_mul_f32_e32 v209, s5, v233
	v_exp_f32_e32 v202, v202
	v_exp_f32_e32 v203, v203
	v_exp_f32_e32 v204, v204
	v_exp_f32_e32 v205, v205
	v_exp_f32_e32 v206, v206
	v_exp_f32_e32 v207, v207
	v_exp_f32_e32 v208, v208
	v_exp_f32_e32 v209, v209
	v_add_f32_e32 v202, 1.0, v202
	v_add_f32_e32 v203, 1.0, v203
	v_add_f32_e32 v204, 1.0, v204
	v_add_f32_e32 v205, 1.0, v205
	v_add_f32_e32 v206, 1.0, v206
	v_add_f32_e32 v207, 1.0, v207
	v_add_f32_e32 v208, 1.0, v208
	v_add_f32_e32 v209, 1.0, v209
	v_rcp_f32_e32 v202, v202
	v_rcp_f32_e32 v203, v203
	v_rcp_f32_e32 v204, v204
	v_rcp_f32_e32 v205, v205
	v_rcp_f32_e32 v206, v206
	v_rcp_f32_e32 v207, v207
	v_rcp_f32_e32 v208, v208
	v_rcp_f32_e32 v209, v209
	v_mul_f32_e32 v202, v222, v202
	v_mul_f32_e32 v203, v223, v203
	v_mul_f32_e32 v204, v224, v204
	v_mul_f32_e32 v205, v225, v205
	v_mul_f32_e32 v206, v226, v206
	v_mul_f32_e32 v207, v227, v207
	v_mul_f32_e32 v208, v232, v208
	v_mul_f32_e32 v209, v233, v209
	v_cvt_pk_bf16_f32 v228, v202, v203
	v_cvt_pk_bf16_f32 v229, v204, v205
	v_cvt_pk_bf16_f32 v230, v206, v207
	v_cvt_pk_bf16_f32 v231, v208, v209
	global_store_dwordx4 v[134:135], v[228:231], off
	s_branch .Lp2e_b0_done
; DI u32x4 pack8(const float* x) { u32x4 v; v.x = cvt_pk(x[0], x[1]); v.y = cvt_pk(x[2], x[3]); v.z = cvt_pk(x[4], x[5]); v.w = cvt_pk(x[6], x[7]); return v; }
; DI float sigmoidf_(float v) { return __builtin_amdgcn_rcpf(1.0f + __expf(-v)); }
;     DI void operator()(const f32x4 (&acc)[2][2][4][2], const Unit& u, int wr, int wc, int fr, int fq) const {
;     ...
;         for (int bj = 0; bj < 2; ++bj) {
;             const int colw = u.pn * BM + bj * HALF + wc * 32;
;             const int act = colw < C_SILU ? 0 : (colw < C_GATE ? 1 : 2);
; #pragma unroll
;             for (int ai = 0; ai < 2; ++ai)
; #pragma unroll
;                 for (int m = 0; m < 4; ++m) {
;                     float v[8];
; #pragma unroll
;                     for (int j = 0; j < 4; ++j) { v[j] = acc[ai][bj][m][0][j] * rstd[ai][m]; v[4 + j] = acc[ai][bj][m][1][j] * rstd[ai][m]; }
;                     if (act) {
; #pragma unroll
;                         for (int j = 0; j < 8; ++j) { const float sg = sigmoidf_(v[j]); v[j] = act == 1 ? v[j] * sg : sg; }
;                     }
;                     *(u32x4*)(O + (size_t)(row0 + ai * HALF + m * 16) * LDP + col0 + bj * HALF) = pack8(v);
;                 }
.Lp2e_b0_act0:
	v_mul_f32_e32 v176, v124, v172
	v_mul_f32_e32 v177, v125, v172
	v_mul_f32_e32 v178, v126, v172
	v_mul_f32_e32 v179, v127, v172
	v_mul_f32_e32 v180, v120, v172
	v_mul_f32_e32 v181, v121, v172
	v_mul_f32_e32 v182, v122, v172
	v_mul_f32_e32 v183, v123, v172
	v_cvt_pk_bf16_f32 v184, v176, v177
	v_cvt_pk_bf16_f32 v185, v178, v179
	v_cvt_pk_bf16_f32 v186, v180, v181
	v_cvt_pk_bf16_f32 v187, v182, v183
	global_store_dwordx4 v[134:135], v[184:187], off
	v_lshl_add_u64 v[134:135], v[134:135], 0, s[6:7]
	v_mul_f32_e32 v202, v108, v168
	v_mul_f32_e32 v203, v109, v168
	v_mul_f32_e32 v204, v110, v168
	v_mul_f32_e32 v205, v111, v168
	v_mul_f32_e32 v206, v104, v168
	v_mul_f32_e32 v207, v105, v168
	v_mul_f32_e32 v208, v106, v168
	v_mul_f32_e32 v209, v107, v168
	v_cvt_pk_bf16_f32 v228, v202, v203
	v_cvt_pk_bf16_f32 v229, v204, v205
	v_cvt_pk_bf16_f32 v230, v206, v207
	v_cvt_pk_bf16_f32 v231, v208, v209
	global_store_dwordx4 v[134:135], v[228:231], off
	v_lshl_add_u64 v[134:135], v[134:135], 0, s[6:7]
	v_mul_f32_e32 v176, v92, v166
	v_mul_f32_e32 v177, v93, v166
	v_mul_f32_e32 v178, v94, v166
	v_mul_f32_e32 v179, v95, v166
	v_mul_f32_e32 v180, v88, v166
	v_mul_f32_e32 v181, v89, v166
	v_mul_f32_e32 v182, v90, v166
	v_mul_f32_e32 v183, v91, v166
	v_cvt_pk_bf16_f32 v184, v176, v177
	v_cvt_pk_bf16_f32 v185, v178, v179
	v_cvt_pk_bf16_f32 v186, v180, v181
	v_cvt_pk_bf16_f32 v187, v182, v183
	global_store_dwordx4 v[134:135], v[184:187], off
	v_lshl_add_u64 v[134:135], v[134:135], 0, s[6:7]
	v_mul_f32_e32 v202, v76, v164
	v_mul_f32_e32 v203, v77, v164
	v_mul_f32_e32 v204, v78, v164
	v_mul_f32_e32 v205, v79, v164
	v_mul_f32_e32 v206, v72, v164
	v_mul_f32_e32 v207, v73, v164
	v_mul_f32_e32 v208, v74, v164
	v_mul_f32_e32 v209, v75, v164
	v_cvt_pk_bf16_f32 v228, v202, v203
	v_cvt_pk_bf16_f32 v229, v204, v205
	v_cvt_pk_bf16_f32 v230, v206, v207
	v_cvt_pk_bf16_f32 v231, v208, v209
	global_store_dwordx4 v[134:135], v[228:231], off
	v_lshl_add_u64 v[134:135], v[134:135], 0, s[2:3]
	v_mul_f32_e32 v176, v60, v162
	v_mul_f32_e32 v177, v61, v162
	v_mul_f32_e32 v178, v62, v162
	v_mul_f32_e32 v179, v63, v162
	v_mul_f32_e32 v180, v56, v162
	v_mul_f32_e32 v181, v57, v162
	v_mul_f32_e32 v182, v58, v162
	v_mul_f32_e32 v183, v59, v162
	v_cvt_pk_bf16_f32 v184, v176, v177
	v_cvt_pk_bf16_f32 v185, v178, v179
	v_cvt_pk_bf16_f32 v186, v180, v181
	v_cvt_pk_bf16_f32 v187, v182, v183
	global_store_dwordx4 v[134:135], v[184:187], off
	v_lshl_add_u64 v[134:135], v[134:135], 0, s[6:7]
	v_mul_f32_e32 v202, v44, v160
	v_mul_f32_e32 v203, v45, v160
	v_mul_f32_e32 v204, v46, v160
	v_mul_f32_e32 v205, v47, v160
	v_mul_f32_e32 v206, v40, v160
	v_mul_f32_e32 v207, v41, v160
	v_mul_f32_e32 v208, v42, v160
	v_mul_f32_e32 v209, v43, v160
	v_cvt_pk_bf16_f32 v228, v202, v203
	v_cvt_pk_bf16_f32 v229, v204, v205
	v_cvt_pk_bf16_f32 v230, v206, v207
	v_cvt_pk_bf16_f32 v231, v208, v209
	global_store_dwordx4 v[134:135], v[228:231], off
	v_lshl_add_u64 v[134:135], v[134:135], 0, s[6:7]
	v_mul_f32_e32 v176, v28, v158
	v_mul_f32_e32 v177, v29, v158
	v_mul_f32_e32 v178, v30, v158
	v_mul_f32_e32 v179, v31, v158
	v_mul_f32_e32 v180, v24, v158
	v_mul_f32_e32 v181, v25, v158
	v_mul_f32_e32 v182, v26, v158
	v_mul_f32_e32 v183, v27, v158
	v_cvt_pk_bf16_f32 v184, v176, v177
	v_cvt_pk_bf16_f32 v185, v178, v179
	v_cvt_pk_bf16_f32 v186, v180, v181
	v_cvt_pk_bf16_f32 v187, v182, v183
	global_store_dwordx4 v[134:135], v[184:187], off
	v_lshl_add_u64 v[134:135], v[134:135], 0, s[6:7]
	v_mul_f32_e32 v202, v12, v156
	v_mul_f32_e32 v203, v13, v156
	v_mul_f32_e32 v204, v14, v156
	v_mul_f32_e32 v205, v15, v156
	v_mul_f32_e32 v206, v8, v156
	v_mul_f32_e32 v207, v9, v156
	v_mul_f32_e32 v208, v10, v156
	v_mul_f32_e32 v209, v11, v156
	v_cvt_pk_bf16_f32 v228, v202, v203
	v_cvt_pk_bf16_f32 v229, v204, v205
	v_cvt_pk_bf16_f32 v230, v206, v207
	v_cvt_pk_bf16_f32 v231, v208, v209
	global_store_dwordx4 v[134:135], v[228:231], off
.Lp2e_b0_done:
	s_bitset1_b32 s8, 7
	v_mov_b64_e32 v[134:135], v[132:133]
	s_cmpk_lt_i32 s8, 0x1da0
	s_cbranch_scc1 .Lp2e_b1_act0
	s_cmpk_lt_i32 s8, 0x25a0
	s_cbranch_scc1 .Lp2e_b1_act1
	v_mul_f32_e32 v176, v116, v172
	v_mul_f32_e32 v177, v117, v172
	v_mul_f32_e32 v178, v118, v172
	v_mul_f32_e32 v179, v119, v172
	v_mul_f32_e32 v180, v112, v172
	v_mul_f32_e32 v181, v113, v172
	v_mul_f32_e32 v182, v114, v172
	v_mul_f32_e32 v183, v115, v172
	v_mul_f32_e32 v176, s5, v176
	v_mul_f32_e32 v177, s5, v177
	v_mul_f32_e32 v178, s5, v178
	v_mul_f32_e32 v179, s5, v179
	v_mul_f32_e32 v180, s5, v180
	v_mul_f32_e32 v181, s5, v181
	v_mul_f32_e32 v182, s5, v182
	v_mul_f32_e32 v183, s5, v183
	v_exp_f32_e32 v176, v176
	v_exp_f32_e32 v177, v177
	v_exp_f32_e32 v178, v178
	v_exp_f32_e32 v179, v179
	v_exp_f32_e32 v180, v180
	v_exp_f32_e32 v181, v181
	v_exp_f32_e32 v182, v182
	v_exp_f32_e32 v183, v183
	v_add_f32_e32 v176, 1.0, v176
	v_add_f32_e32 v177, 1.0, v177
	v_add_f32_e32 v178, 1.0, v178
	v_add_f32_e32 v179, 1.0, v179
	v_add_f32_e32 v180, 1.0, v180
	v_add_f32_e32 v181, 1.0, v181
	v_add_f32_e32 v182, 1.0, v182
	v_add_f32_e32 v183, 1.0, v183
	v_rcp_f32_e32 v176, v176
	v_rcp_f32_e32 v177, v177
	v_rcp_f32_e32 v178, v178
	v_rcp_f32_e32 v179, v179
	v_rcp_f32_e32 v180, v180
	v_rcp_f32_e32 v181, v181
	v_rcp_f32_e32 v182, v182
	v_rcp_f32_e32 v183, v183
	v_cvt_pk_bf16_f32 v184, v176, v177
	v_cvt_pk_bf16_f32 v185, v178, v179
	v_cvt_pk_bf16_f32 v186, v180, v181
	v_cvt_pk_bf16_f32 v187, v182, v183
	global_store_dwordx4 v[134:135], v[184:187], off offset:256
	v_lshl_add_u64 v[134:135], v[134:135], 0, s[6:7]
	v_mul_f32_e32 v202, v100, v168
	v_mul_f32_e32 v203, v101, v168
	v_mul_f32_e32 v204, v102, v168
	v_mul_f32_e32 v205, v103, v168
; DI u32x4 pack8(const float* x) { u32x4 v; v.x = cvt_pk(x[0], x[1]); v.y = cvt_pk(x[2], x[3]); v.z = cvt_pk(x[4], x[5]); v.w = cvt_pk(x[6], x[7]); return v; }
; DI float sigmoidf_(float v) { return __builtin_amdgcn_rcpf(1.0f + __expf(-v)); }
;     DI void operator()(const f32x4 (&acc)[2][2][4][2], const Unit& u, int wr, int wc, int fr, int fq) const {
;     ...
;         for (int bj = 0; bj < 2; ++bj) {
;             const int colw = u.pn * BM + bj * HALF + wc * 32;
;             const int act = colw < C_SILU ? 0 : (colw < C_GATE ? 1 : 2);
; #pragma unroll
;             for (int ai = 0; ai < 2; ++ai)
; #pragma unroll
;                 for (int m = 0; m < 4; ++m) {
;                     float v[8];
; #pragma unroll
;                     for (int j = 0; j < 4; ++j) { v[j] = acc[ai][bj][m][0][j] * rstd[ai][m]; v[4 + j] = acc[ai][bj][m][1][j] * rstd[ai][m]; }
;                     if (act) {
; #pragma unroll
;                         for (int j = 0; j < 8; ++j) { const float sg = sigmoidf_(v[j]); v[j] = act == 1 ? v[j] * sg : sg; }
;                     }
;                     *(u32x4*)(O + (size_t)(row0 + ai * HALF + m * 16) * LDP + col0 + bj * HALF) = pack8(v);
;                 }
	v_mul_f32_e32 v206, v96, v168
	v_mul_f32_e32 v207, v97, v168
	v_mul_f32_e32 v208, v98, v168
	v_mul_f32_e32 v209, v99, v168
	v_mul_f32_e32 v202, s5, v202
	v_mul_f32_e32 v203, s5, v203
	v_mul_f32_e32 v204, s5, v204
	v_mul_f32_e32 v205, s5, v205
	v_mul_f32_e32 v206, s5, v206
	v_mul_f32_e32 v207, s5, v207
	v_mul_f32_e32 v208, s5, v208
	v_mul_f32_e32 v209, s5, v209
	v_exp_f32_e32 v202, v202
	v_exp_f32_e32 v203, v203
	v_exp_f32_e32 v204, v204
	v_exp_f32_e32 v205, v205
	v_exp_f32_e32 v206, v206
	v_exp_f32_e32 v207, v207
	v_exp_f32_e32 v208, v208
	v_exp_f32_e32 v209, v209
	v_add_f32_e32 v202, 1.0, v202
	v_add_f32_e32 v203, 1.0, v203
	v_add_f32_e32 v204, 1.0, v204
	v_add_f32_e32 v205, 1.0, v205
	v_add_f32_e32 v206, 1.0, v206
	v_add_f32_e32 v207, 1.0, v207
	v_add_f32_e32 v208, 1.0, v208
	v_add_f32_e32 v209, 1.0, v209
	v_rcp_f32_e32 v202, v202
	v_rcp_f32_e32 v203, v203
	v_rcp_f32_e32 v204, v204
	v_rcp_f32_e32 v205, v205
	v_rcp_f32_e32 v206, v206
	v_rcp_f32_e32 v207, v207
	v_rcp_f32_e32 v208, v208
	v_rcp_f32_e32 v209, v209
	v_cvt_pk_bf16_f32 v228, v202, v203
	v_cvt_pk_bf16_f32 v229, v204, v205
	v_cvt_pk_bf16_f32 v230, v206, v207
	v_cvt_pk_bf16_f32 v231, v208, v209
	global_store_dwordx4 v[134:135], v[228:231], off offset:256
	v_lshl_add_u64 v[134:135], v[134:135], 0, s[6:7]
	v_mul_f32_e32 v176, v84, v166
	v_mul_f32_e32 v177, v85, v166
	v_mul_f32_e32 v178, v86, v166
	v_mul_f32_e32 v179, v87, v166
	v_mul_f32_e32 v180, v80, v166
	v_mul_f32_e32 v181, v81, v166
	v_mul_f32_e32 v182, v82, v166
	v_mul_f32_e32 v183, v83, v166
	v_mul_f32_e32 v176, s5, v176
	v_mul_f32_e32 v177, s5, v177
	v_mul_f32_e32 v178, s5, v178
	v_mul_f32_e32 v179, s5, v179
	v_mul_f32_e32 v180, s5, v180
	v_mul_f32_e32 v181, s5, v181
	v_mul_f32_e32 v182, s5, v182
	v_mul_f32_e32 v183, s5, v183
	v_exp_f32_e32 v176, v176
	v_exp_f32_e32 v177, v177
	v_exp_f32_e32 v178, v178
	v_exp_f32_e32 v179, v179
	v_exp_f32_e32 v180, v180
	v_exp_f32_e32 v181, v181
	v_exp_f32_e32 v182, v182
	v_exp_f32_e32 v183, v183
	v_add_f32_e32 v176, 1.0, v176
	v_add_f32_e32 v177, 1.0, v177
	v_add_f32_e32 v178, 1.0, v178
	v_add_f32_e32 v179, 1.0, v179
	v_add_f32_e32 v180, 1.0, v180
	v_add_f32_e32 v181, 1.0, v181
	v_add_f32_e32 v182, 1.0, v182
	v_add_f32_e32 v183, 1.0, v183
	v_rcp_f32_e32 v176, v176
	v_rcp_f32_e32 v177, v177
	v_rcp_f32_e32 v178, v178
	v_rcp_f32_e32 v179, v179
	v_rcp_f32_e32 v180, v180
	v_rcp_f32_e32 v181, v181
	v_rcp_f32_e32 v182, v182
	v_rcp_f32_e32 v183, v183
	v_cvt_pk_bf16_f32 v184, v176, v177
	v_cvt_pk_bf16_f32 v185, v178, v179
	v_cvt_pk_bf16_f32 v186, v180, v181
	v_cvt_pk_bf16_f32 v187, v182, v183
	global_store_dwordx4 v[134:135], v[184:187], off offset:256
	v_lshl_add_u64 v[134:135], v[134:135], 0, s[6:7]
	v_mul_f32_e32 v202, v68, v164
	v_mul_f32_e32 v203, v69, v164
	v_mul_f32_e32 v204, v70, v164
	v_mul_f32_e32 v205, v71, v164
	v_mul_f32_e32 v206, v64, v164
	v_mul_f32_e32 v207, v65, v164
	v_mul_f32_e32 v208, v66, v164
	v_mul_f32_e32 v209, v67, v164
	v_mul_f32_e32 v202, s5, v202
	v_mul_f32_e32 v203, s5, v203
	v_mul_f32_e32 v204, s5, v204
	v_mul_f32_e32 v205, s5, v205
	v_mul_f32_e32 v206, s5, v206
	v_mul_f32_e32 v207, s5, v207
	v_mul_f32_e32 v208, s5, v208
	v_mul_f32_e32 v209, s5, v209
	v_exp_f32_e32 v202, v202
	v_exp_f32_e32 v203, v203
	v_exp_f32_e32 v204, v204
	v_exp_f32_e32 v205, v205
	v_exp_f32_e32 v206, v206
	v_exp_f32_e32 v207, v207
	v_exp_f32_e32 v208, v208
	v_exp_f32_e32 v209, v209
	v_add_f32_e32 v202, 1.0, v202
	v_add_f32_e32 v203, 1.0, v203
	v_add_f32_e32 v204, 1.0, v204
	v_add_f32_e32 v205, 1.0, v205
	v_add_f32_e32 v206, 1.0, v206
	v_add_f32_e32 v207, 1.0, v207
	v_add_f32_e32 v208, 1.0, v208
	v_add_f32_e32 v209, 1.0, v209
	v_rcp_f32_e32 v202, v202
	v_rcp_f32_e32 v203, v203
	v_rcp_f32_e32 v204, v204
	v_rcp_f32_e32 v205, v205
	v_rcp_f32_e32 v206, v206
	v_rcp_f32_e32 v207, v207
	v_rcp_f32_e32 v208, v208
	v_rcp_f32_e32 v209, v209
	v_cvt_pk_bf16_f32 v228, v202, v203
	v_cvt_pk_bf16_f32 v229, v204, v205
	v_cvt_pk_bf16_f32 v230, v206, v207
	v_cvt_pk_bf16_f32 v231, v208, v209
	global_store_dwordx4 v[134:135], v[228:231], off offset:256
	v_lshl_add_u64 v[134:135], v[134:135], 0, s[2:3]
	v_mul_f32_e32 v176, v52, v162
	v_mul_f32_e32 v177, v53, v162
	v_mul_f32_e32 v178, v54, v162
	v_mul_f32_e32 v179, v55, v162
	v_mul_f32_e32 v180, v48, v162
	v_mul_f32_e32 v181, v49, v162
	v_mul_f32_e32 v182, v50, v162
	v_mul_f32_e32 v183, v51, v162
	v_mul_f32_e32 v176, s5, v176
	v_mul_f32_e32 v177, s5, v177
	v_mul_f32_e32 v178, s5, v178
	v_mul_f32_e32 v179, s5, v179
	v_mul_f32_e32 v180, s5, v180
	v_mul_f32_e32 v181, s5, v181
	v_mul_f32_e32 v182, s5, v182
	v_mul_f32_e32 v183, s5, v183
	v_exp_f32_e32 v176, v176
	v_exp_f32_e32 v177, v177
	v_exp_f32_e32 v178, v178
	v_exp_f32_e32 v179, v179
	v_exp_f32_e32 v180, v180
	v_exp_f32_e32 v181, v181
	v_exp_f32_e32 v182, v182
	v_exp_f32_e32 v183, v183
	v_add_f32_e32 v176, 1.0, v176
	v_add_f32_e32 v177, 1.0, v177
	v_add_f32_e32 v178, 1.0, v178
	v_add_f32_e32 v179, 1.0, v179
	v_add_f32_e32 v180, 1.0, v180
	v_add_f32_e32 v181, 1.0, v181
	v_add_f32_e32 v182, 1.0, v182
	v_add_f32_e32 v183, 1.0, v183
	v_rcp_f32_e32 v176, v176
	v_rcp_f32_e32 v177, v177
	v_rcp_f32_e32 v178, v178
	v_rcp_f32_e32 v179, v179
	v_rcp_f32_e32 v180, v180
	v_rcp_f32_e32 v181, v181
	v_rcp_f32_e32 v182, v182
	v_rcp_f32_e32 v183, v183
	v_cvt_pk_bf16_f32 v184, v176, v177
	v_cvt_pk_bf16_f32 v185, v178, v179
	v_cvt_pk_bf16_f32 v186, v180, v181
	v_cvt_pk_bf16_f32 v187, v182, v183
	global_store_dwordx4 v[134:135], v[184:187], off offset:256
	v_lshl_add_u64 v[134:135], v[134:135], 0, s[6:7]
	v_mul_f32_e32 v202, v36, v160
	v_mul_f32_e32 v203, v37, v160
	v_mul_f32_e32 v204, v38, v160
	v_mul_f32_e32 v205, v39, v160
; DI u32x4 pack8(const float* x) { u32x4 v; v.x = cvt_pk(x[0], x[1]); v.y = cvt_pk(x[2], x[3]); v.z = cvt_pk(x[4], x[5]); v.w = cvt_pk(x[6], x[7]); return v; }
; DI float sigmoidf_(float v) { return __builtin_amdgcn_rcpf(1.0f + __expf(-v)); }
;     DI void operator()(const f32x4 (&acc)[2][2][4][2], const Unit& u, int wr, int wc, int fr, int fq) const {
;     ...
;         for (int bj = 0; bj < 2; ++bj) {
;             const int colw = u.pn * BM + bj * HALF + wc * 32;
;             const int act = colw < C_SILU ? 0 : (colw < C_GATE ? 1 : 2);
; #pragma unroll
;             for (int ai = 0; ai < 2; ++ai)
; #pragma unroll
;                 for (int m = 0; m < 4; ++m) {
;                     float v[8];
; #pragma unroll
;                     for (int j = 0; j < 4; ++j) { v[j] = acc[ai][bj][m][0][j] * rstd[ai][m]; v[4 + j] = acc[ai][bj][m][1][j] * rstd[ai][m]; }
;                     if (act) {
; #pragma unroll
;                         for (int j = 0; j < 8; ++j) { const float sg = sigmoidf_(v[j]); v[j] = act == 1 ? v[j] * sg : sg; }
;                     }
;                     *(u32x4*)(O + (size_t)(row0 + ai * HALF + m * 16) * LDP + col0 + bj * HALF) = pack8(v);
;                 }
	v_mul_f32_e32 v206, v32, v160
	v_mul_f32_e32 v207, v33, v160
	v_mul_f32_e32 v208, v34, v160
	v_mul_f32_e32 v209, v35, v160
	v_mul_f32_e32 v202, s5, v202
	v_mul_f32_e32 v203, s5, v203
	v_mul_f32_e32 v204, s5, v204
	v_mul_f32_e32 v205, s5, v205
	v_mul_f32_e32 v206, s5, v206
	v_mul_f32_e32 v207, s5, v207
	v_mul_f32_e32 v208, s5, v208
	v_mul_f32_e32 v209, s5, v209
	v_exp_f32_e32 v202, v202
	v_exp_f32_e32 v203, v203
	v_exp_f32_e32 v204, v204
	v_exp_f32_e32 v205, v205
	v_exp_f32_e32 v206, v206
	v_exp_f32_e32 v207, v207
	v_exp_f32_e32 v208, v208
	v_exp_f32_e32 v209, v209
	v_add_f32_e32 v202, 1.0, v202
	v_add_f32_e32 v203, 1.0, v203
	v_add_f32_e32 v204, 1.0, v204
	v_add_f32_e32 v205, 1.0, v205
	v_add_f32_e32 v206, 1.0, v206
	v_add_f32_e32 v207, 1.0, v207
	v_add_f32_e32 v208, 1.0, v208
	v_add_f32_e32 v209, 1.0, v209
	v_rcp_f32_e32 v202, v202
	v_rcp_f32_e32 v203, v203
	v_rcp_f32_e32 v204, v204
	v_rcp_f32_e32 v205, v205
	v_rcp_f32_e32 v206, v206
	v_rcp_f32_e32 v207, v207
	v_rcp_f32_e32 v208, v208
	v_rcp_f32_e32 v209, v209
	v_cvt_pk_bf16_f32 v228, v202, v203
	v_cvt_pk_bf16_f32 v229, v204, v205
	v_cvt_pk_bf16_f32 v230, v206, v207
	v_cvt_pk_bf16_f32 v231, v208, v209
	global_store_dwordx4 v[134:135], v[228:231], off offset:256
	v_lshl_add_u64 v[134:135], v[134:135], 0, s[6:7]
	v_mul_f32_e32 v176, v20, v158
	v_mul_f32_e32 v177, v21, v158
	v_mul_f32_e32 v178, v22, v158
	v_mul_f32_e32 v179, v23, v158
	v_mul_f32_e32 v180, v16, v158
	v_mul_f32_e32 v181, v17, v158
	v_mul_f32_e32 v182, v18, v158
	v_mul_f32_e32 v183, v19, v158
	v_mul_f32_e32 v176, s5, v176
	v_mul_f32_e32 v177, s5, v177
	v_mul_f32_e32 v178, s5, v178
	v_mul_f32_e32 v179, s5, v179
	v_mul_f32_e32 v180, s5, v180
	v_mul_f32_e32 v181, s5, v181
	v_mul_f32_e32 v182, s5, v182
	v_mul_f32_e32 v183, s5, v183
	v_exp_f32_e32 v176, v176
	v_exp_f32_e32 v177, v177
	v_exp_f32_e32 v178, v178
	v_exp_f32_e32 v179, v179
	v_exp_f32_e32 v180, v180
	v_exp_f32_e32 v181, v181
	v_exp_f32_e32 v182, v182
	v_exp_f32_e32 v183, v183
	v_add_f32_e32 v176, 1.0, v176
	v_add_f32_e32 v177, 1.0, v177
	v_add_f32_e32 v178, 1.0, v178
	v_add_f32_e32 v179, 1.0, v179
	v_add_f32_e32 v180, 1.0, v180
	v_add_f32_e32 v181, 1.0, v181
	v_add_f32_e32 v182, 1.0, v182
	v_add_f32_e32 v183, 1.0, v183
	v_rcp_f32_e32 v176, v176
	v_rcp_f32_e32 v177, v177
	v_rcp_f32_e32 v178, v178
	v_rcp_f32_e32 v179, v179
	v_rcp_f32_e32 v180, v180
	v_rcp_f32_e32 v181, v181
	v_rcp_f32_e32 v182, v182
	v_rcp_f32_e32 v183, v183
	v_cvt_pk_bf16_f32 v184, v176, v177
	v_cvt_pk_bf16_f32 v185, v178, v179
	v_cvt_pk_bf16_f32 v186, v180, v181
	v_cvt_pk_bf16_f32 v187, v182, v183
	global_store_dwordx4 v[134:135], v[184:187], off offset:256
	v_lshl_add_u64 v[134:135], v[134:135], 0, s[6:7]
	v_mul_f32_e32 v202, v4, v156
	v_mul_f32_e32 v203, v5, v156
	v_mul_f32_e32 v204, v6, v156
	v_mul_f32_e32 v205, v7, v156
	v_mul_f32_e32 v206, v0, v156
	v_mul_f32_e32 v207, v1, v156
	v_mul_f32_e32 v208, v2, v156
	v_mul_f32_e32 v209, v3, v156
	v_mul_f32_e32 v202, s5, v202
	v_mul_f32_e32 v203, s5, v203
	v_mul_f32_e32 v204, s5, v204
	v_mul_f32_e32 v205, s5, v205
	v_mul_f32_e32 v206, s5, v206
	v_mul_f32_e32 v207, s5, v207
	v_mul_f32_e32 v208, s5, v208
	v_mul_f32_e32 v209, s5, v209
	v_exp_f32_e32 v202, v202
	v_exp_f32_e32 v203, v203
	v_exp_f32_e32 v204, v204
	v_exp_f32_e32 v205, v205
	v_exp_f32_e32 v206, v206
	v_exp_f32_e32 v207, v207
	v_exp_f32_e32 v208, v208
	v_exp_f32_e32 v209, v209
	v_add_f32_e32 v202, 1.0, v202
	v_add_f32_e32 v203, 1.0, v203
	v_add_f32_e32 v204, 1.0, v204
	v_add_f32_e32 v205, 1.0, v205
	v_add_f32_e32 v206, 1.0, v206
	v_add_f32_e32 v207, 1.0, v207
	v_add_f32_e32 v208, 1.0, v208
	v_add_f32_e32 v209, 1.0, v209
	v_rcp_f32_e32 v202, v202
	v_rcp_f32_e32 v203, v203
	v_rcp_f32_e32 v204, v204
	v_rcp_f32_e32 v205, v205
	v_rcp_f32_e32 v206, v206
	v_rcp_f32_e32 v207, v207
	v_rcp_f32_e32 v208, v208
	v_rcp_f32_e32 v209, v209
	v_cvt_pk_bf16_f32 v228, v202, v203
	v_cvt_pk_bf16_f32 v229, v204, v205
	v_cvt_pk_bf16_f32 v230, v206, v207
	v_cvt_pk_bf16_f32 v231, v208, v209
	global_store_dwordx4 v[134:135], v[228:231], off offset:256
	s_branch .Lp2e_b1_done
.Lp2e_b1_act1:
	v_mul_f32_e32 v188, v116, v172
	v_mul_f32_e32 v189, v117, v172
	v_mul_f32_e32 v190, v118, v172
	v_mul_f32_e32 v191, v119, v172
	v_mul_f32_e32 v192, v112, v172
	v_mul_f32_e32 v193, v113, v172
	v_mul_f32_e32 v194, v114, v172
	v_mul_f32_e32 v195, v115, v172
	v_mul_f32_e32 v176, s5, v188
	v_mul_f32_e32 v177, s5, v189
	v_mul_f32_e32 v178, s5, v190
	v_mul_f32_e32 v179, s5, v191
	v_mul_f32_e32 v180, s5, v192
	v_mul_f32_e32 v181, s5, v193
	v_mul_f32_e32 v182, s5, v194
	v_mul_f32_e32 v183, s5, v195
	v_exp_f32_e32 v176, v176
	v_exp_f32_e32 v177, v177
	v_exp_f32_e32 v178, v178
	v_exp_f32_e32 v179, v179
	v_exp_f32_e32 v180, v180
	v_exp_f32_e32 v181, v181
	v_exp_f32_e32 v182, v182
	v_exp_f32_e32 v183, v183
	v_add_f32_e32 v176, 1.0, v176
	v_add_f32_e32 v177, 1.0, v177
	v_add_f32_e32 v178, 1.0, v178
	v_add_f32_e32 v179, 1.0, v179
	v_add_f32_e32 v180, 1.0, v180
	v_add_f32_e32 v181, 1.0, v181
	v_add_f32_e32 v182, 1.0, v182
	v_add_f32_e32 v183, 1.0, v183
	v_rcp_f32_e32 v176, v176
	v_rcp_f32_e32 v177, v177
	v_rcp_f32_e32 v178, v178
	v_rcp_f32_e32 v179, v179
	v_rcp_f32_e32 v180, v180
	v_rcp_f32_e32 v181, v181
	v_rcp_f32_e32 v182, v182
	v_rcp_f32_e32 v183, v183
	v_mul_f32_e32 v176, v188, v176
	v_mul_f32_e32 v177, v189, v177
	v_mul_f32_e32 v178, v190, v178
	v_mul_f32_e32 v179, v191, v179
	v_mul_f32_e32 v180, v192, v180
	v_mul_f32_e32 v181, v193, v181
	v_mul_f32_e32 v182, v194, v182
	v_mul_f32_e32 v183, v195, v183
	v_cvt_pk_bf16_f32 v184, v176, v177
	v_cvt_pk_bf16_f32 v185, v178, v179
	v_cvt_pk_bf16_f32 v186, v180, v181
	v_cvt_pk_bf16_f32 v187, v182, v183
; DI u32x4 pack8(const float* x) { u32x4 v; v.x = cvt_pk(x[0], x[1]); v.y = cvt_pk(x[2], x[3]); v.z = cvt_pk(x[4], x[5]); v.w = cvt_pk(x[6], x[7]); return v; }
; DI float sigmoidf_(float v) { return __builtin_amdgcn_rcpf(1.0f + __expf(-v)); }
;     DI void operator()(const f32x4 (&acc)[2][2][4][2], const Unit& u, int wr, int wc, int fr, int fq) const {
;     ...
;         for (int bj = 0; bj < 2; ++bj) {
;             const int colw = u.pn * BM + bj * HALF + wc * 32;
;             const int act = colw < C_SILU ? 0 : (colw < C_GATE ? 1 : 2);
; #pragma unroll
;             for (int ai = 0; ai < 2; ++ai)
; #pragma unroll
;                 for (int m = 0; m < 4; ++m) {
;                     float v[8];
; #pragma unroll
;                     for (int j = 0; j < 4; ++j) { v[j] = acc[ai][bj][m][0][j] * rstd[ai][m]; v[4 + j] = acc[ai][bj][m][1][j] * rstd[ai][m]; }
;                     if (act) {
; #pragma unroll
;                         for (int j = 0; j < 8; ++j) { const float sg = sigmoidf_(v[j]); v[j] = act == 1 ? v[j] * sg : sg; }
;                     }
;                     *(u32x4*)(O + (size_t)(row0 + ai * HALF + m * 16) * LDP + col0 + bj * HALF) = pack8(v);
;                 }
	global_store_dwordx4 v[134:135], v[184:187], off offset:256
	v_lshl_add_u64 v[134:135], v[134:135], 0, s[6:7]
	v_mul_f32_e32 v222, v100, v168
	v_mul_f32_e32 v223, v101, v168
	v_mul_f32_e32 v224, v102, v168
	v_mul_f32_e32 v225, v103, v168
	v_mul_f32_e32 v226, v96, v168
	v_mul_f32_e32 v227, v97, v168
	v_mul_f32_e32 v232, v98, v168
	v_mul_f32_e32 v233, v99, v168
	v_mul_f32_e32 v202, s5, v222
	v_mul_f32_e32 v203, s5, v223
	v_mul_f32_e32 v204, s5, v224
	v_mul_f32_e32 v205, s5, v225
	v_mul_f32_e32 v206, s5, v226
	v_mul_f32_e32 v207, s5, v227
	v_mul_f32_e32 v208, s5, v232
	v_mul_f32_e32 v209, s5, v233
	v_exp_f32_e32 v202, v202
	v_exp_f32_e32 v203, v203
	v_exp_f32_e32 v204, v204
	v_exp_f32_e32 v205, v205
	v_exp_f32_e32 v206, v206
	v_exp_f32_e32 v207, v207
	v_exp_f32_e32 v208, v208
	v_exp_f32_e32 v209, v209
	v_add_f32_e32 v202, 1.0, v202
	v_add_f32_e32 v203, 1.0, v203
	v_add_f32_e32 v204, 1.0, v204
	v_add_f32_e32 v205, 1.0, v205
	v_add_f32_e32 v206, 1.0, v206
	v_add_f32_e32 v207, 1.0, v207
	v_add_f32_e32 v208, 1.0, v208
	v_add_f32_e32 v209, 1.0, v209
	v_rcp_f32_e32 v202, v202
	v_rcp_f32_e32 v203, v203
	v_rcp_f32_e32 v204, v204
	v_rcp_f32_e32 v205, v205
	v_rcp_f32_e32 v206, v206
	v_rcp_f32_e32 v207, v207
	v_rcp_f32_e32 v208, v208
	v_rcp_f32_e32 v209, v209
	v_mul_f32_e32 v202, v222, v202
	v_mul_f32_e32 v203, v223, v203
	v_mul_f32_e32 v204, v224, v204
	v_mul_f32_e32 v205, v225, v205
	v_mul_f32_e32 v206, v226, v206
	v_mul_f32_e32 v207, v227, v207
	v_mul_f32_e32 v208, v232, v208
	v_mul_f32_e32 v209, v233, v209
	v_cvt_pk_bf16_f32 v228, v202, v203
	v_cvt_pk_bf16_f32 v229, v204, v205
	v_cvt_pk_bf16_f32 v230, v206, v207
	v_cvt_pk_bf16_f32 v231, v208, v209
	global_store_dwordx4 v[134:135], v[228:231], off offset:256
	v_lshl_add_u64 v[134:135], v[134:135], 0, s[6:7]
	v_mul_f32_e32 v188, v84, v166
	v_mul_f32_e32 v189, v85, v166
	v_mul_f32_e32 v190, v86, v166
	v_mul_f32_e32 v191, v87, v166
	v_mul_f32_e32 v192, v80, v166
	v_mul_f32_e32 v193, v81, v166
	v_mul_f32_e32 v194, v82, v166
	v_mul_f32_e32 v195, v83, v166
	v_mul_f32_e32 v176, s5, v188
	v_mul_f32_e32 v177, s5, v189
	v_mul_f32_e32 v178, s5, v190
	v_mul_f32_e32 v179, s5, v191
	v_mul_f32_e32 v180, s5, v192
	v_mul_f32_e32 v181, s5, v193
	v_mul_f32_e32 v182, s5, v194
	v_mul_f32_e32 v183, s5, v195
	v_exp_f32_e32 v176, v176
	v_exp_f32_e32 v177, v177
	v_exp_f32_e32 v178, v178
	v_exp_f32_e32 v179, v179
	v_exp_f32_e32 v180, v180
	v_exp_f32_e32 v181, v181
	v_exp_f32_e32 v182, v182
	v_exp_f32_e32 v183, v183
	v_add_f32_e32 v176, 1.0, v176
	v_add_f32_e32 v177, 1.0, v177
	v_add_f32_e32 v178, 1.0, v178
	v_add_f32_e32 v179, 1.0, v179
	v_add_f32_e32 v180, 1.0, v180
	v_add_f32_e32 v181, 1.0, v181
	v_add_f32_e32 v182, 1.0, v182
	v_add_f32_e32 v183, 1.0, v183
	v_rcp_f32_e32 v176, v176
	v_rcp_f32_e32 v177, v177
	v_rcp_f32_e32 v178, v178
	v_rcp_f32_e32 v179, v179
	v_rcp_f32_e32 v180, v180
	v_rcp_f32_e32 v181, v181
	v_rcp_f32_e32 v182, v182
	v_rcp_f32_e32 v183, v183
	v_mul_f32_e32 v176, v188, v176
	v_mul_f32_e32 v177, v189, v177
	v_mul_f32_e32 v178, v190, v178
	v_mul_f32_e32 v179, v191, v179
	v_mul_f32_e32 v180, v192, v180
	v_mul_f32_e32 v181, v193, v181
	v_mul_f32_e32 v182, v194, v182
	v_mul_f32_e32 v183, v195, v183
	v_cvt_pk_bf16_f32 v184, v176, v177
	v_cvt_pk_bf16_f32 v185, v178, v179
	v_cvt_pk_bf16_f32 v186, v180, v181
	v_cvt_pk_bf16_f32 v187, v182, v183
	global_store_dwordx4 v[134:135], v[184:187], off offset:256
	v_lshl_add_u64 v[134:135], v[134:135], 0, s[6:7]
	v_mul_f32_e32 v222, v68, v164
	v_mul_f32_e32 v223, v69, v164
	v_mul_f32_e32 v224, v70, v164
	v_mul_f32_e32 v225, v71, v164
	v_mul_f32_e32 v226, v64, v164
	v_mul_f32_e32 v227, v65, v164
	v_mul_f32_e32 v232, v66, v164
	v_mul_f32_e32 v233, v67, v164
	v_mul_f32_e32 v202, s5, v222
	v_mul_f32_e32 v203, s5, v223
	v_mul_f32_e32 v204, s5, v224
	v_mul_f32_e32 v205, s5, v225
	v_mul_f32_e32 v206, s5, v226
	v_mul_f32_e32 v207, s5, v227
	v_mul_f32_e32 v208, s5, v232
	v_mul_f32_e32 v209, s5, v233
	v_exp_f32_e32 v202, v202
	v_exp_f32_e32 v203, v203
	v_exp_f32_e32 v204, v204
	v_exp_f32_e32 v205, v205
	v_exp_f32_e32 v206, v206
	v_exp_f32_e32 v207, v207
	v_exp_f32_e32 v208, v208
	v_exp_f32_e32 v209, v209
	v_add_f32_e32 v202, 1.0, v202
	v_add_f32_e32 v203, 1.0, v203
	v_add_f32_e32 v204, 1.0, v204
	v_add_f32_e32 v205, 1.0, v205
	v_add_f32_e32 v206, 1.0, v206
	v_add_f32_e32 v207, 1.0, v207
	v_add_f32_e32 v208, 1.0, v208
	v_add_f32_e32 v209, 1.0, v209
	v_rcp_f32_e32 v202, v202
	v_rcp_f32_e32 v203, v203
	v_rcp_f32_e32 v204, v204
	v_rcp_f32_e32 v205, v205
	v_rcp_f32_e32 v206, v206
	v_rcp_f32_e32 v207, v207
	v_rcp_f32_e32 v208, v208
	v_rcp_f32_e32 v209, v209
	v_mul_f32_e32 v202, v222, v202
	v_mul_f32_e32 v203, v223, v203
	v_mul_f32_e32 v204, v224, v204
	v_mul_f32_e32 v205, v225, v205
	v_mul_f32_e32 v206, v226, v206
	v_mul_f32_e32 v207, v227, v207
	v_mul_f32_e32 v208, v232, v208
	v_mul_f32_e32 v209, v233, v209
	v_cvt_pk_bf16_f32 v228, v202, v203
	v_cvt_pk_bf16_f32 v229, v204, v205
	v_cvt_pk_bf16_f32 v230, v206, v207
	v_cvt_pk_bf16_f32 v231, v208, v209
	global_store_dwordx4 v[134:135], v[228:231], off offset:256
	v_lshl_add_u64 v[134:135], v[134:135], 0, s[2:3]
	v_mul_f32_e32 v188, v52, v162
	v_mul_f32_e32 v189, v53, v162
	v_mul_f32_e32 v190, v54, v162
	v_mul_f32_e32 v191, v55, v162
	v_mul_f32_e32 v192, v48, v162
	v_mul_f32_e32 v193, v49, v162
	v_mul_f32_e32 v194, v50, v162
	v_mul_f32_e32 v195, v51, v162
	v_mul_f32_e32 v176, s5, v188
	v_mul_f32_e32 v177, s5, v189
	v_mul_f32_e32 v178, s5, v190
	v_mul_f32_e32 v179, s5, v191
	v_mul_f32_e32 v180, s5, v192
	v_mul_f32_e32 v181, s5, v193
	v_mul_f32_e32 v182, s5, v194
	v_mul_f32_e32 v183, s5, v195
	v_exp_f32_e32 v176, v176
	v_exp_f32_e32 v177, v177
; DI u32x4 pack8(const float* x) { u32x4 v; v.x = cvt_pk(x[0], x[1]); v.y = cvt_pk(x[2], x[3]); v.z = cvt_pk(x[4], x[5]); v.w = cvt_pk(x[6], x[7]); return v; }
; DI float sigmoidf_(float v) { return __builtin_amdgcn_rcpf(1.0f + __expf(-v)); }
;     DI void operator()(const f32x4 (&acc)[2][2][4][2], const Unit& u, int wr, int wc, int fr, int fq) const {
;     ...
;         for (int bj = 0; bj < 2; ++bj) {
;             const int colw = u.pn * BM + bj * HALF + wc * 32;
;             const int act = colw < C_SILU ? 0 : (colw < C_GATE ? 1 : 2);
; #pragma unroll
;             for (int ai = 0; ai < 2; ++ai)
; #pragma unroll
;                 for (int m = 0; m < 4; ++m) {
;                     float v[8];
; #pragma unroll
;                     for (int j = 0; j < 4; ++j) { v[j] = acc[ai][bj][m][0][j] * rstd[ai][m]; v[4 + j] = acc[ai][bj][m][1][j] * rstd[ai][m]; }
;                     if (act) {
; #pragma unroll
;                         for (int j = 0; j < 8; ++j) { const float sg = sigmoidf_(v[j]); v[j] = act == 1 ? v[j] * sg : sg; }
;                     }
;                     *(u32x4*)(O + (size_t)(row0 + ai * HALF + m * 16) * LDP + col0 + bj * HALF) = pack8(v);
;                 }
	v_exp_f32_e32 v178, v178
	v_exp_f32_e32 v179, v179
	v_exp_f32_e32 v180, v180
	v_exp_f32_e32 v181, v181
	v_exp_f32_e32 v182, v182
	v_exp_f32_e32 v183, v183
	v_add_f32_e32 v176, 1.0, v176
	v_add_f32_e32 v177, 1.0, v177
	v_add_f32_e32 v178, 1.0, v178
	v_add_f32_e32 v179, 1.0, v179
	v_add_f32_e32 v180, 1.0, v180
	v_add_f32_e32 v181, 1.0, v181
	v_add_f32_e32 v182, 1.0, v182
	v_add_f32_e32 v183, 1.0, v183
	v_rcp_f32_e32 v176, v176
	v_rcp_f32_e32 v177, v177
	v_rcp_f32_e32 v178, v178
	v_rcp_f32_e32 v179, v179
	v_rcp_f32_e32 v180, v180
	v_rcp_f32_e32 v181, v181
	v_rcp_f32_e32 v182, v182
	v_rcp_f32_e32 v183, v183
	v_mul_f32_e32 v176, v188, v176
	v_mul_f32_e32 v177, v189, v177
	v_mul_f32_e32 v178, v190, v178
	v_mul_f32_e32 v179, v191, v179
	v_mul_f32_e32 v180, v192, v180
	v_mul_f32_e32 v181, v193, v181
	v_mul_f32_e32 v182, v194, v182
	v_mul_f32_e32 v183, v195, v183
	v_cvt_pk_bf16_f32 v184, v176, v177
	v_cvt_pk_bf16_f32 v185, v178, v179
	v_cvt_pk_bf16_f32 v186, v180, v181
	v_cvt_pk_bf16_f32 v187, v182, v183
	global_store_dwordx4 v[134:135], v[184:187], off offset:256
	v_lshl_add_u64 v[134:135], v[134:135], 0, s[6:7]
	v_mul_f32_e32 v222, v36, v160
	v_mul_f32_e32 v223, v37, v160
	v_mul_f32_e32 v224, v38, v160
	v_mul_f32_e32 v225, v39, v160
	v_mul_f32_e32 v226, v32, v160
	v_mul_f32_e32 v227, v33, v160
	v_mul_f32_e32 v232, v34, v160
	v_mul_f32_e32 v233, v35, v160
	v_mul_f32_e32 v202, s5, v222
	v_mul_f32_e32 v203, s5, v223
	v_mul_f32_e32 v204, s5, v224
	v_mul_f32_e32 v205, s5, v225
	v_mul_f32_e32 v206, s5, v226
	v_mul_f32_e32 v207, s5, v227
	v_mul_f32_e32 v208, s5, v232
	v_mul_f32_e32 v209, s5, v233
	v_exp_f32_e32 v202, v202
	v_exp_f32_e32 v203, v203
	v_exp_f32_e32 v204, v204
	v_exp_f32_e32 v205, v205
	v_exp_f32_e32 v206, v206
	v_exp_f32_e32 v207, v207
	v_exp_f32_e32 v208, v208
	v_exp_f32_e32 v209, v209
	v_add_f32_e32 v202, 1.0, v202
	v_add_f32_e32 v203, 1.0, v203
	v_add_f32_e32 v204, 1.0, v204
	v_add_f32_e32 v205, 1.0, v205
	v_add_f32_e32 v206, 1.0, v206
	v_add_f32_e32 v207, 1.0, v207
	v_add_f32_e32 v208, 1.0, v208
	v_add_f32_e32 v209, 1.0, v209
	v_rcp_f32_e32 v202, v202
	v_rcp_f32_e32 v203, v203
	v_rcp_f32_e32 v204, v204
	v_rcp_f32_e32 v205, v205
	v_rcp_f32_e32 v206, v206
	v_rcp_f32_e32 v207, v207
	v_rcp_f32_e32 v208, v208
	v_rcp_f32_e32 v209, v209
	v_mul_f32_e32 v202, v222, v202
	v_mul_f32_e32 v203, v223, v203
	v_mul_f32_e32 v204, v224, v204
	v_mul_f32_e32 v205, v225, v205
	v_mul_f32_e32 v206, v226, v206
	v_mul_f32_e32 v207, v227, v207
	v_mul_f32_e32 v208, v232, v208
	v_mul_f32_e32 v209, v233, v209
	v_cvt_pk_bf16_f32 v228, v202, v203
	v_cvt_pk_bf16_f32 v229, v204, v205
	v_cvt_pk_bf16_f32 v230, v206, v207
	v_cvt_pk_bf16_f32 v231, v208, v209
	global_store_dwordx4 v[134:135], v[228:231], off offset:256
	v_lshl_add_u64 v[134:135], v[134:135], 0, s[6:7]
	v_mul_f32_e32 v188, v20, v158
	v_mul_f32_e32 v189, v21, v158
	v_mul_f32_e32 v190, v22, v158
	v_mul_f32_e32 v191, v23, v158
	v_mul_f32_e32 v192, v16, v158
	v_mul_f32_e32 v193, v17, v158
	v_mul_f32_e32 v194, v18, v158
	v_mul_f32_e32 v195, v19, v158
	v_mul_f32_e32 v176, s5, v188
	v_mul_f32_e32 v177, s5, v189
	v_mul_f32_e32 v178, s5, v190
	v_mul_f32_e32 v179, s5, v191
	v_mul_f32_e32 v180, s5, v192
	v_mul_f32_e32 v181, s5, v193
	v_mul_f32_e32 v182, s5, v194
	v_mul_f32_e32 v183, s5, v195
	v_exp_f32_e32 v176, v176
	v_exp_f32_e32 v177, v177
	v_exp_f32_e32 v178, v178
	v_exp_f32_e32 v179, v179
	v_exp_f32_e32 v180, v180
	v_exp_f32_e32 v181, v181
	v_exp_f32_e32 v182, v182
	v_exp_f32_e32 v183, v183
	v_add_f32_e32 v176, 1.0, v176
	v_add_f32_e32 v177, 1.0, v177
	v_add_f32_e32 v178, 1.0, v178
	v_add_f32_e32 v179, 1.0, v179
	v_add_f32_e32 v180, 1.0, v180
	v_add_f32_e32 v181, 1.0, v181
	v_add_f32_e32 v182, 1.0, v182
	v_add_f32_e32 v183, 1.0, v183
	v_rcp_f32_e32 v176, v176
	v_rcp_f32_e32 v177, v177
	v_rcp_f32_e32 v178, v178
	v_rcp_f32_e32 v179, v179
	v_rcp_f32_e32 v180, v180
	v_rcp_f32_e32 v181, v181
	v_rcp_f32_e32 v182, v182
	v_rcp_f32_e32 v183, v183
	v_mul_f32_e32 v176, v188, v176
	v_mul_f32_e32 v177, v189, v177
	v_mul_f32_e32 v178, v190, v178
	v_mul_f32_e32 v179, v191, v179
	v_mul_f32_e32 v180, v192, v180
	v_mul_f32_e32 v181, v193, v181
	v_mul_f32_e32 v182, v194, v182
	v_mul_f32_e32 v183, v195, v183
	v_cvt_pk_bf16_f32 v184, v176, v177
	v_cvt_pk_bf16_f32 v185, v178, v179
	v_cvt_pk_bf16_f32 v186, v180, v181
	v_cvt_pk_bf16_f32 v187, v182, v183
	global_store_dwordx4 v[134:135], v[184:187], off offset:256
	v_lshl_add_u64 v[134:135], v[134:135], 0, s[6:7]
	v_mul_f32_e32 v222, v4, v156
	v_mul_f32_e32 v223, v5, v156
	v_mul_f32_e32 v224, v6, v156
	v_mul_f32_e32 v225, v7, v156
	v_mul_f32_e32 v226, v0, v156
	v_mul_f32_e32 v227, v1, v156
	v_mul_f32_e32 v232, v2, v156
	v_mul_f32_e32 v233, v3, v156
	v_mul_f32_e32 v202, s5, v222
	v_mul_f32_e32 v203, s5, v223
	v_mul_f32_e32 v204, s5, v224
	v_mul_f32_e32 v205, s5, v225
	v_mul_f32_e32 v206, s5, v226
	v_mul_f32_e32 v207, s5, v227
	v_mul_f32_e32 v208, s5, v232
	v_mul_f32_e32 v209, s5, v233
	v_exp_f32_e32 v202, v202
	v_exp_f32_e32 v203, v203
	v_exp_f32_e32 v204, v204
	v_exp_f32_e32 v205, v205
	v_exp_f32_e32 v206, v206
	v_exp_f32_e32 v207, v207
	v_exp_f32_e32 v208, v208
	v_exp_f32_e32 v209, v209
	v_add_f32_e32 v202, 1.0, v202
	v_add_f32_e32 v203, 1.0, v203
	v_add_f32_e32 v204, 1.0, v204
	v_add_f32_e32 v205, 1.0, v205
	v_add_f32_e32 v206, 1.0, v206
	v_add_f32_e32 v207, 1.0, v207
	v_add_f32_e32 v208, 1.0, v208
	v_add_f32_e32 v209, 1.0, v209
	v_rcp_f32_e32 v202, v202
	v_rcp_f32_e32 v203, v203
	v_rcp_f32_e32 v204, v204
	v_rcp_f32_e32 v205, v205
	v_rcp_f32_e32 v206, v206
	v_rcp_f32_e32 v207, v207
	v_rcp_f32_e32 v208, v208
	v_rcp_f32_e32 v209, v209
	v_mul_f32_e32 v202, v222, v202
	v_mul_f32_e32 v203, v223, v203
	v_mul_f32_e32 v204, v224, v204
	v_mul_f32_e32 v205, v225, v205
	v_mul_f32_e32 v206, v226, v206
	v_mul_f32_e32 v207, v227, v207
	v_mul_f32_e32 v208, v232, v208
	v_mul_f32_e32 v209, v233, v209
	v_cvt_pk_bf16_f32 v228, v202, v203
	v_cvt_pk_bf16_f32 v229, v204, v205
	v_cvt_pk_bf16_f32 v230, v206, v207
	v_cvt_pk_bf16_f32 v231, v208, v209
	global_store_dwordx4 v[134:135], v[228:231], off offset:256
	s_branch .Lp2e_b1_done
;     DI HeadInfo head(int idx) const {
;         HeadInfo h; h.dstride = 64; h.scale = 1.f; h.rope = false;
;         if (idx < 8) { h.wv = gqa_n; h.dst = Qb + (size_t)idx * S * 64; h.scale = 0.125f * LOG2E; h.rope = true; }
;         else if (idx < 10) { h.wv = gqa_n + 64; h.dst = Kb + (size_t)(idx - 8) * S * 64; h.rope = true; }
;         else if (idx < 34) { const int j = idx - 10; h.wv = dil_n + (j >> 3) * 64; h.dst = Qc + (size_t)j * S * 64; h.scale = 0.125f * LOG2E; }
;         else if (idx < 58) { const int j = idx - 34; h.wv = dil_n + (3 + (j >> 3)) * 64; h.dst = Kc + (size_t)j * S * 64; }
;         else if (idx < 66) { const int j = idx - 58; h.wv = diff_n; h.dst = Qd + (size_t)(j >> 1) * S * 128 + (j & 1) * 64; h.dstride = 128; h.scale = 0.125f * LOG2E; }
;         else { const int j = idx - 66; h.wv = diff_n + 64; h.dst = Kd + (size_t)(j >> 1) * S * 128 + (j & 1) * 64; h.dstride = 128; }
;         return h;
;     }
;     DI void operator()(const f32x4 (&acc)[2][2][4][2], const Unit& u, int wr, int wc, int fr, int fq) const {
;         int row0 = u.pm * BM + wr * 64 + fr, col0 = u.pn * BM + wc * 32 + 8 * fq;
;         asm volatile("" : "+v"(row0), "+v"(col0));
;         float rstd[2][4];
; #pragma unroll
;         for (int ai = 0; ai < 2; ++ai)
; #pragma unroll
;             for (int m = 0; m < 4; ++m) rstd[ai][m] = rsqrtf(ssq[row0 + ai * HALF + m * 16] * (1.0f / DM) + EPS);
;         if (u.pn < NHT) {
;             const int hs = 4 * u.pn + wc;
;             if (hs >= 74) return;
;             const HeadInfo hd = head(hs);
;     ...
;         for (int bj = 0; bj < 2; ++bj) {
;             const int colw = u.pn * BM + bj * HALF + wc * 32;
;             const int act = colw < C_SILU ? 0 : (colw < C_GATE ? 1 : 2);
; #pragma unroll
;             for (int ai = 0; ai < 2; ++ai)
; #pragma unroll
;                 for (int m = 0; m < 4; ++m) {
;                     float v[8];
; #pragma unroll
;                     for (int j = 0; j < 4; ++j) { v[j] = acc[ai][bj][m][0][j] * rstd[ai][m]; v[4 + j] = acc[ai][bj][m][1][j] * rstd[ai][m]; }
;                     if (act) {
; #pragma unroll
;                         for (int j = 0; j < 8; ++j) { const float sg = sigmoidf_(v[j]); v[j] = act == 1 ? v[j] * sg : sg; }
;                     }
;                     *(u32x4*)(O + (size_t)(row0 + ai * HALF + m * 16) * LDP + col0 + bj * HALF) = pack8(v);
;                 }
.Lp2e_b1_act0:
	v_mul_f32_e32 v176, v116, v172
	v_mul_f32_e32 v177, v117, v172
	v_mul_f32_e32 v178, v118, v172
	v_mul_f32_e32 v179, v119, v172
	v_mul_f32_e32 v180, v112, v172
	v_mul_f32_e32 v181, v113, v172
	v_mul_f32_e32 v182, v114, v172
	v_mul_f32_e32 v183, v115, v172
	v_cvt_pk_bf16_f32 v184, v176, v177
	v_cvt_pk_bf16_f32 v185, v178, v179
	v_cvt_pk_bf16_f32 v186, v180, v181
	v_cvt_pk_bf16_f32 v187, v182, v183
	global_store_dwordx4 v[134:135], v[184:187], off offset:256
	v_lshl_add_u64 v[134:135], v[134:135], 0, s[6:7]
	v_mul_f32_e32 v202, v100, v168
	v_mul_f32_e32 v203, v101, v168
	v_mul_f32_e32 v204, v102, v168
	v_mul_f32_e32 v205, v103, v168
	v_mul_f32_e32 v206, v96, v168
	v_mul_f32_e32 v207, v97, v168
	v_mul_f32_e32 v208, v98, v168
	v_mul_f32_e32 v209, v99, v168
	v_cvt_pk_bf16_f32 v228, v202, v203
	v_cvt_pk_bf16_f32 v229, v204, v205
	v_cvt_pk_bf16_f32 v230, v206, v207
	v_cvt_pk_bf16_f32 v231, v208, v209
	global_store_dwordx4 v[134:135], v[228:231], off offset:256
	v_lshl_add_u64 v[134:135], v[134:135], 0, s[6:7]
	v_mul_f32_e32 v176, v84, v166
	v_mul_f32_e32 v177, v85, v166
	v_mul_f32_e32 v178, v86, v166
	v_mul_f32_e32 v179, v87, v166
	v_mul_f32_e32 v180, v80, v166
	v_mul_f32_e32 v181, v81, v166
	v_mul_f32_e32 v182, v82, v166
	v_mul_f32_e32 v183, v83, v166
	v_cvt_pk_bf16_f32 v184, v176, v177
	v_cvt_pk_bf16_f32 v185, v178, v179
	v_cvt_pk_bf16_f32 v186, v180, v181
	v_cvt_pk_bf16_f32 v187, v182, v183
	global_store_dwordx4 v[134:135], v[184:187], off offset:256
	v_lshl_add_u64 v[134:135], v[134:135], 0, s[6:7]
	v_mul_f32_e32 v202, v68, v164
	v_mul_f32_e32 v203, v69, v164
	v_mul_f32_e32 v204, v70, v164
	v_mul_f32_e32 v205, v71, v164
	v_mul_f32_e32 v206, v64, v164
	v_mul_f32_e32 v207, v65, v164
	v_mul_f32_e32 v208, v66, v164
	v_mul_f32_e32 v209, v67, v164
	v_cvt_pk_bf16_f32 v228, v202, v203
	v_cvt_pk_bf16_f32 v229, v204, v205
	v_cvt_pk_bf16_f32 v230, v206, v207
	v_cvt_pk_bf16_f32 v231, v208, v209
	global_store_dwordx4 v[134:135], v[228:231], off offset:256
	v_lshl_add_u64 v[134:135], v[134:135], 0, s[2:3]
	v_mul_f32_e32 v176, v52, v162
	v_mul_f32_e32 v177, v53, v162
	v_mul_f32_e32 v178, v54, v162
	v_mul_f32_e32 v179, v55, v162
	v_mul_f32_e32 v180, v48, v162
	v_mul_f32_e32 v181, v49, v162
	v_mul_f32_e32 v182, v50, v162
	v_mul_f32_e32 v183, v51, v162
	v_cvt_pk_bf16_f32 v184, v176, v177
	v_cvt_pk_bf16_f32 v185, v178, v179
	v_cvt_pk_bf16_f32 v186, v180, v181
	v_cvt_pk_bf16_f32 v187, v182, v183
	global_store_dwordx4 v[134:135], v[184:187], off offset:256
	v_lshl_add_u64 v[134:135], v[134:135], 0, s[6:7]
	v_mul_f32_e32 v202, v36, v160
	v_mul_f32_e32 v203, v37, v160
	v_mul_f32_e32 v204, v38, v160
	v_mul_f32_e32 v205, v39, v160
	v_mul_f32_e32 v206, v32, v160
	v_mul_f32_e32 v207, v33, v160
	v_mul_f32_e32 v208, v34, v160
	v_mul_f32_e32 v209, v35, v160
	v_cvt_pk_bf16_f32 v228, v202, v203
	v_cvt_pk_bf16_f32 v229, v204, v205
	v_cvt_pk_bf16_f32 v230, v206, v207
	v_cvt_pk_bf16_f32 v231, v208, v209
	global_store_dwordx4 v[134:135], v[228:231], off offset:256
	v_lshl_add_u64 v[134:135], v[134:135], 0, s[6:7]
	v_mul_f32_e32 v176, v20, v158
	v_mul_f32_e32 v177, v21, v158
	v_mul_f32_e32 v178, v22, v158
	v_mul_f32_e32 v179, v23, v158
	v_mul_f32_e32 v180, v16, v158
	v_mul_f32_e32 v181, v17, v158
	v_mul_f32_e32 v182, v18, v158
	v_mul_f32_e32 v183, v19, v158
	v_cvt_pk_bf16_f32 v184, v176, v177
	v_cvt_pk_bf16_f32 v185, v178, v179
	v_cvt_pk_bf16_f32 v186, v180, v181
	v_cvt_pk_bf16_f32 v187, v182, v183
	global_store_dwordx4 v[134:135], v[184:187], off offset:256
	v_lshl_add_u64 v[134:135], v[134:135], 0, s[6:7]
	v_mul_f32_e32 v202, v4, v156
	v_mul_f32_e32 v203, v5, v156
	v_mul_f32_e32 v204, v6, v156
	v_mul_f32_e32 v205, v7, v156
	v_mul_f32_e32 v206, v0, v156
	v_mul_f32_e32 v207, v1, v156
	v_mul_f32_e32 v208, v2, v156
	v_mul_f32_e32 v209, v3, v156
	v_cvt_pk_bf16_f32 v228, v202, v203
	v_cvt_pk_bf16_f32 v229, v204, v205
	v_cvt_pk_bf16_f32 v230, v206, v207
	v_cvt_pk_bf16_f32 v231, v208, v209
	global_store_dwordx4 v[134:135], v[228:231], off offset:256
.Lp2e_b1_done:
	s_mov_b64 s[2:3], 0
.LBB0_199:
	s_and_b64 vcc, exec, s[2:3]
	s_cbranch_vccz .LBB0_253
	s_lshl_b32 s2, s10, 2
	s_or_b32 s4, s2, s82
	s_cmpk_gt_i32 s4, 0x49
	s_cbranch_scc1 .LBB0_253
	s_cmp_gt_i32 s4, 7
	s_mov_b64 s[20:21], -1
	s_cbranch_scc0 .LBB0_218
	s_cmp_gt_u32 s4, 9
	s_mov_b64 s[10:11], -1
	s_cbranch_scc0 .LBB0_216
	s_cmp_gt_u32 s4, 33
	s_cbranch_scc0 .LBB0_213
	s_cmp_gt_u32 s4, 57
	s_mov_b64 s[2:3], -1
	s_cbranch_scc0 .LBB0_210
	s_cmpk_gt_u32 s4, 0x41
	s_cbranch_scc0 .LBB0_207
	s_add_i32 s2, s4, 0xffffffbe
	s_lshr_b32 s14, s2, 1
	s_lshl_b64 s[2:3], s[14:15], 21
	v_readlane_b32 s5, v255, 15
	s_add_u32 s2, s5, s2
	v_readlane_b32 s5, v255, 16
	s_addc_u32 s3, s5, s3
	s_lshl_b32 s5, s4, 7
	s_and_b32 s5, s5, 0x80
	s_add_u32 s6, s2, s5
	s_addc_u32 s7, s3, 0
	s_mov_b64 s[2:3], 0
